# peer_v cross-row reduction: ds_bpermute+cndmask butterfly replaced by v_permlane32/16_swap + bank-masked DPP adds
# speedup vs baseline: 1.1284x; 1.0065x over previous
.LBB0_689:
	s_or_b64 exec, exec, s[26:27]
	s_waitcnt vmcnt(15)
	v_cvt_pk_f32_fp8_e32 v[146:147], v0
	v_cvt_pk_f32_fp8_sdwa v[236:237], v0 src0_sel:WORD_1
	v_cvt_pk_f32_fp8_e32 v[238:239], v1
	v_cvt_pk_f32_fp8_sdwa v[240:241], v1 src0_sel:WORD_1
	v_cvt_pk_f32_fp8_e32 v[242:243], v2
	v_cvt_pk_f32_fp8_sdwa v[244:245], v2 src0_sel:WORD_1
	v_cvt_pk_f32_fp8_e32 v[246:247], v3
	v_cvt_pk_f32_fp8_sdwa v[248:249], v3 src0_sel:WORD_1
	s_waitcnt vmcnt(14)
	v_cvt_pk_f32_fp8_e32 v[250:251], v4
	v_and_b32_e32 v128, 0xffff0000, v161
	v_pk_fma_f32 v[146:147], v[128:129], v[146:147], 0 op_sel_hi:[0,1,0]
	v_pk_fma_f32 v[236:237], v[128:129], v[236:237], 0 op_sel_hi:[0,1,0]
	v_pk_fma_f32 v[238:239], v[128:129], v[238:239], 0 op_sel_hi:[0,1,0]
	v_pk_fma_f32 v[240:241], v[128:129], v[240:241], 0 op_sel_hi:[0,1,0]
	v_pk_fma_f32 v[242:243], v[128:129], v[242:243], 0 op_sel_hi:[0,1,0]
	v_pk_fma_f32 v[244:245], v[128:129], v[244:245], 0 op_sel_hi:[0,1,0]
	v_pk_fma_f32 v[246:247], v[128:129], v[246:247], 0 op_sel_hi:[0,1,0]
	v_pk_fma_f32 v[248:249], v[128:129], v[248:249], 0 op_sel_hi:[0,1,0]
	v_and_b32_e32 v128, 0xffff0000, v163
	v_pk_fma_f32 v[146:147], v[128:129], v[250:251], v[146:147] op_sel_hi:[0,1,1]
	v_cvt_pk_f32_fp8_sdwa v[250:251], v4 src0_sel:WORD_1
	v_ashrrev_i32_e32 v143, 31, v142
	v_pk_fma_f32 v[236:237], v[128:129], v[250:251], v[236:237] op_sel_hi:[0,1,1]
	v_cvt_pk_f32_fp8_e32 v[250:251], v5
	v_pk_fma_f32 v[238:239], v[128:129], v[250:251], v[238:239] op_sel_hi:[0,1,1]
	v_cvt_pk_f32_fp8_sdwa v[250:251], v5 src0_sel:WORD_1
	v_pk_fma_f32 v[240:241], v[128:129], v[250:251], v[240:241] op_sel_hi:[0,1,1]
	v_cvt_pk_f32_fp8_e32 v[250:251], v6
	v_pk_fma_f32 v[242:243], v[128:129], v[250:251], v[242:243] op_sel_hi:[0,1,1]
	v_cvt_pk_f32_fp8_sdwa v[250:251], v6 src0_sel:WORD_1
	v_pk_fma_f32 v[244:245], v[128:129], v[250:251], v[244:245] op_sel_hi:[0,1,1]
	v_cvt_pk_f32_fp8_e32 v[250:251], v7
	v_pk_fma_f32 v[246:247], v[128:129], v[250:251], v[246:247] op_sel_hi:[0,1,1]
	v_cvt_pk_f32_fp8_sdwa v[250:251], v7 src0_sel:WORD_1
	v_pk_fma_f32 v[248:249], v[128:129], v[250:251], v[248:249] op_sel_hi:[0,1,1]
	s_waitcnt vmcnt(13)
	v_cvt_pk_f32_fp8_e32 v[250:251], v8
	v_and_b32_e32 v128, 0xffff0000, v183
	v_pk_fma_f32 v[146:147], v[128:129], v[250:251], v[146:147] op_sel_hi:[0,1,1]
	v_cvt_pk_f32_fp8_sdwa v[250:251], v8 src0_sel:WORD_1
	v_pk_fma_f32 v[236:237], v[128:129], v[250:251], v[236:237] op_sel_hi:[0,1,1]
	v_cvt_pk_f32_fp8_e32 v[250:251], v9
	v_pk_fma_f32 v[238:239], v[128:129], v[250:251], v[238:239] op_sel_hi:[0,1,1]
	v_cvt_pk_f32_fp8_sdwa v[250:251], v9 src0_sel:WORD_1
	v_pk_fma_f32 v[240:241], v[128:129], v[250:251], v[240:241] op_sel_hi:[0,1,1]
	v_cvt_pk_f32_fp8_e32 v[250:251], v10
	v_pk_fma_f32 v[242:243], v[128:129], v[250:251], v[242:243] op_sel_hi:[0,1,1]
	v_cvt_pk_f32_fp8_sdwa v[250:251], v10 src0_sel:WORD_1
	v_pk_fma_f32 v[244:245], v[128:129], v[250:251], v[244:245] op_sel_hi:[0,1,1]
	v_cvt_pk_f32_fp8_e32 v[250:251], v11
	v_pk_fma_f32 v[246:247], v[128:129], v[250:251], v[246:247] op_sel_hi:[0,1,1]
	v_cvt_pk_f32_fp8_sdwa v[250:251], v11 src0_sel:WORD_1
	v_pk_fma_f32 v[248:249], v[128:129], v[250:251], v[248:249] op_sel_hi:[0,1,1]
	s_waitcnt vmcnt(12)
	v_cvt_pk_f32_fp8_e32 v[250:251], v12
	v_and_b32_e32 v128, 0xffff0000, v187
	v_pk_fma_f32 v[146:147], v[128:129], v[250:251], v[146:147] op_sel_hi:[0,1,1]
	v_cvt_pk_f32_fp8_sdwa v[250:251], v12 src0_sel:WORD_1
	v_pk_fma_f32 v[236:237], v[128:129], v[250:251], v[236:237] op_sel_hi:[0,1,1]
	v_cvt_pk_f32_fp8_e32 v[250:251], v13
	v_pk_fma_f32 v[238:239], v[128:129], v[250:251], v[238:239] op_sel_hi:[0,1,1]
	v_cvt_pk_f32_fp8_sdwa v[250:251], v13 src0_sel:WORD_1
	v_pk_fma_f32 v[240:241], v[128:129], v[250:251], v[240:241] op_sel_hi:[0,1,1]
	v_cvt_pk_f32_fp8_e32 v[250:251], v14
	v_pk_fma_f32 v[242:243], v[128:129], v[250:251], v[242:243] op_sel_hi:[0,1,1]
	v_cvt_pk_f32_fp8_sdwa v[250:251], v14 src0_sel:WORD_1
	v_pk_fma_f32 v[244:245], v[128:129], v[250:251], v[244:245] op_sel_hi:[0,1,1]
	v_cvt_pk_f32_fp8_e32 v[250:251], v15
	v_pk_fma_f32 v[246:247], v[128:129], v[250:251], v[246:247] op_sel_hi:[0,1,1]
	v_cvt_pk_f32_fp8_sdwa v[250:251], v15 src0_sel:WORD_1
	v_pk_fma_f32 v[248:249], v[128:129], v[250:251], v[248:249] op_sel_hi:[0,1,1]
	s_waitcnt vmcnt(11)
	v_cvt_pk_f32_fp8_e32 v[250:251], v16
	v_and_b32_e32 v128, 0xffff0000, v188
	v_pk_fma_f32 v[146:147], v[128:129], v[250:251], v[146:147] op_sel_hi:[0,1,1]
	v_cvt_pk_f32_fp8_sdwa v[250:251], v16 src0_sel:WORD_1
	v_pk_fma_f32 v[236:237], v[128:129], v[250:251], v[236:237] op_sel_hi:[0,1,1]
	v_cvt_pk_f32_fp8_e32 v[250:251], v17
	v_pk_fma_f32 v[238:239], v[128:129], v[250:251], v[238:239] op_sel_hi:[0,1,1]
	v_cvt_pk_f32_fp8_sdwa v[250:251], v17 src0_sel:WORD_1
	v_pk_fma_f32 v[240:241], v[128:129], v[250:251], v[240:241] op_sel_hi:[0,1,1]
	v_cvt_pk_f32_fp8_e32 v[250:251], v18
	v_pk_fma_f32 v[242:243], v[128:129], v[250:251], v[242:243] op_sel_hi:[0,1,1]
	v_cvt_pk_f32_fp8_sdwa v[250:251], v18 src0_sel:WORD_1
	v_pk_fma_f32 v[244:245], v[128:129], v[250:251], v[244:245] op_sel_hi:[0,1,1]
	v_cvt_pk_f32_fp8_e32 v[250:251], v19
	v_pk_fma_f32 v[246:247], v[128:129], v[250:251], v[246:247] op_sel_hi:[0,1,1]
	v_cvt_pk_f32_fp8_sdwa v[250:251], v19 src0_sel:WORD_1
	v_pk_fma_f32 v[248:249], v[128:129], v[250:251], v[248:249] op_sel_hi:[0,1,1]
	s_waitcnt vmcnt(10)
	v_cvt_pk_f32_fp8_e32 v[250:251], v20
	v_and_b32_e32 v128, 0xffff0000, v189
	v_pk_fma_f32 v[146:147], v[128:129], v[250:251], v[146:147] op_sel_hi:[0,1,1]
	v_cvt_pk_f32_fp8_sdwa v[250:251], v20 src0_sel:WORD_1
	v_pk_fma_f32 v[236:237], v[128:129], v[250:251], v[236:237] op_sel_hi:[0,1,1]
	v_cvt_pk_f32_fp8_e32 v[250:251], v21
	v_pk_fma_f32 v[238:239], v[128:129], v[250:251], v[238:239] op_sel_hi:[0,1,1]
	v_cvt_pk_f32_fp8_sdwa v[250:251], v21 src0_sel:WORD_1
	v_pk_fma_f32 v[240:241], v[128:129], v[250:251], v[240:241] op_sel_hi:[0,1,1]
	v_cvt_pk_f32_fp8_e32 v[250:251], v22
	v_pk_fma_f32 v[242:243], v[128:129], v[250:251], v[242:243] op_sel_hi:[0,1,1]
	v_cvt_pk_f32_fp8_sdwa v[250:251], v22 src0_sel:WORD_1
	v_pk_fma_f32 v[244:245], v[128:129], v[250:251], v[244:245] op_sel_hi:[0,1,1]
	v_cvt_pk_f32_fp8_e32 v[250:251], v23
	v_pk_fma_f32 v[246:247], v[128:129], v[250:251], v[246:247] op_sel_hi:[0,1,1]
	v_cvt_pk_f32_fp8_sdwa v[250:251], v23 src0_sel:WORD_1
	v_pk_fma_f32 v[248:249], v[128:129], v[250:251], v[248:249] op_sel_hi:[0,1,1]
	s_waitcnt vmcnt(9)
	v_cvt_pk_f32_fp8_e32 v[250:251], v24
	v_and_b32_e32 v128, 0xffff0000, v190
	v_pk_fma_f32 v[146:147], v[128:129], v[250:251], v[146:147] op_sel_hi:[0,1,1]
	v_cvt_pk_f32_fp8_sdwa v[250:251], v24 src0_sel:WORD_1
	v_pk_fma_f32 v[236:237], v[128:129], v[250:251], v[236:237] op_sel_hi:[0,1,1]
	v_cvt_pk_f32_fp8_e32 v[250:251], v25
	v_pk_fma_f32 v[238:239], v[128:129], v[250:251], v[238:239] op_sel_hi:[0,1,1]
	v_cvt_pk_f32_fp8_sdwa v[250:251], v25 src0_sel:WORD_1
	v_pk_fma_f32 v[240:241], v[128:129], v[250:251], v[240:241] op_sel_hi:[0,1,1]
	v_cvt_pk_f32_fp8_e32 v[250:251], v26
	v_pk_fma_f32 v[242:243], v[128:129], v[250:251], v[242:243] op_sel_hi:[0,1,1]
	v_cvt_pk_f32_fp8_sdwa v[250:251], v26 src0_sel:WORD_1
	v_pk_fma_f32 v[244:245], v[128:129], v[250:251], v[244:245] op_sel_hi:[0,1,1]
	v_cvt_pk_f32_fp8_e32 v[250:251], v27
	v_pk_fma_f32 v[246:247], v[128:129], v[250:251], v[246:247] op_sel_hi:[0,1,1]
	v_cvt_pk_f32_fp8_sdwa v[250:251], v27 src0_sel:WORD_1
	v_pk_fma_f32 v[248:249], v[128:129], v[250:251], v[248:249] op_sel_hi:[0,1,1]
	s_waitcnt vmcnt(8)
	v_cvt_pk_f32_fp8_e32 v[250:251], v28
	v_and_b32_e32 v128, 0xffff0000, v191
	v_pk_fma_f32 v[146:147], v[128:129], v[250:251], v[146:147] op_sel_hi:[0,1,1]
	v_cvt_pk_f32_fp8_sdwa v[250:251], v28 src0_sel:WORD_1
	v_pk_fma_f32 v[236:237], v[128:129], v[250:251], v[236:237] op_sel_hi:[0,1,1]
	v_cvt_pk_f32_fp8_e32 v[250:251], v29
	v_pk_fma_f32 v[238:239], v[128:129], v[250:251], v[238:239] op_sel_hi:[0,1,1]
	v_cvt_pk_f32_fp8_sdwa v[250:251], v29 src0_sel:WORD_1
	v_pk_fma_f32 v[240:241], v[128:129], v[250:251], v[240:241] op_sel_hi:[0,1,1]
	v_cvt_pk_f32_fp8_e32 v[250:251], v30
	v_pk_fma_f32 v[242:243], v[128:129], v[250:251], v[242:243] op_sel_hi:[0,1,1]
	v_cvt_pk_f32_fp8_sdwa v[250:251], v30 src0_sel:WORD_1
	v_pk_fma_f32 v[244:245], v[128:129], v[250:251], v[244:245] op_sel_hi:[0,1,1]
	v_cvt_pk_f32_fp8_e32 v[250:251], v31
	v_pk_fma_f32 v[246:247], v[128:129], v[250:251], v[246:247] op_sel_hi:[0,1,1]
	v_cvt_pk_f32_fp8_sdwa v[250:251], v31 src0_sel:WORD_1
	v_pk_fma_f32 v[248:249], v[128:129], v[250:251], v[248:249] op_sel_hi:[0,1,1]
	s_waitcnt vmcnt(7)
	v_cvt_pk_f32_fp8_e32 v[250:251], v32
	v_and_b32_e32 v128, 0xffff0000, v192
	v_pk_fma_f32 v[146:147], v[128:129], v[250:251], v[146:147] op_sel_hi:[0,1,1]
	v_cvt_pk_f32_fp8_sdwa v[250:251], v32 src0_sel:WORD_1
	v_pk_fma_f32 v[236:237], v[128:129], v[250:251], v[236:237] op_sel_hi:[0,1,1]
	v_cvt_pk_f32_fp8_e32 v[250:251], v33
	v_pk_fma_f32 v[238:239], v[128:129], v[250:251], v[238:239] op_sel_hi:[0,1,1]
	v_cvt_pk_f32_fp8_sdwa v[250:251], v33 src0_sel:WORD_1
	v_pk_fma_f32 v[240:241], v[128:129], v[250:251], v[240:241] op_sel_hi:[0,1,1]
	v_cvt_pk_f32_fp8_e32 v[250:251], v34
	v_pk_fma_f32 v[242:243], v[128:129], v[250:251], v[242:243] op_sel_hi:[0,1,1]
	v_cvt_pk_f32_fp8_sdwa v[250:251], v34 src0_sel:WORD_1
	v_pk_fma_f32 v[244:245], v[128:129], v[250:251], v[244:245] op_sel_hi:[0,1,1]
	v_cvt_pk_f32_fp8_e32 v[250:251], v35
	v_pk_fma_f32 v[246:247], v[128:129], v[250:251], v[246:247] op_sel_hi:[0,1,1]
	v_cvt_pk_f32_fp8_sdwa v[250:251], v35 src0_sel:WORD_1
	v_pk_fma_f32 v[248:249], v[128:129], v[250:251], v[248:249] op_sel_hi:[0,1,1]
	s_waitcnt vmcnt(6)
	v_cvt_pk_f32_fp8_e32 v[250:251], v36
	v_and_b32_e32 v128, 0xffff0000, v193
	v_pk_fma_f32 v[146:147], v[128:129], v[250:251], v[146:147] op_sel_hi:[0,1,1]
	v_cvt_pk_f32_fp8_sdwa v[250:251], v36 src0_sel:WORD_1
	v_pk_fma_f32 v[236:237], v[128:129], v[250:251], v[236:237] op_sel_hi:[0,1,1]
	v_cvt_pk_f32_fp8_e32 v[250:251], v37
	v_pk_fma_f32 v[238:239], v[128:129], v[250:251], v[238:239] op_sel_hi:[0,1,1]
	v_cvt_pk_f32_fp8_sdwa v[250:251], v37 src0_sel:WORD_1
	v_pk_fma_f32 v[240:241], v[128:129], v[250:251], v[240:241] op_sel_hi:[0,1,1]
	v_cvt_pk_f32_fp8_e32 v[250:251], v38
	v_pk_fma_f32 v[242:243], v[128:129], v[250:251], v[242:243] op_sel_hi:[0,1,1]
	v_cvt_pk_f32_fp8_sdwa v[250:251], v38 src0_sel:WORD_1
	v_pk_fma_f32 v[244:245], v[128:129], v[250:251], v[244:245] op_sel_hi:[0,1,1]
	v_cvt_pk_f32_fp8_e32 v[250:251], v39
	v_pk_fma_f32 v[246:247], v[128:129], v[250:251], v[246:247] op_sel_hi:[0,1,1]
	v_cvt_pk_f32_fp8_sdwa v[250:251], v39 src0_sel:WORD_1
	v_pk_fma_f32 v[248:249], v[128:129], v[250:251], v[248:249] op_sel_hi:[0,1,1]
	s_waitcnt vmcnt(5)
	v_cvt_pk_f32_fp8_e32 v[250:251], v40
	v_and_b32_e32 v128, 0xffff0000, v194
	v_pk_fma_f32 v[146:147], v[128:129], v[250:251], v[146:147] op_sel_hi:[0,1,1]
	v_cvt_pk_f32_fp8_sdwa v[250:251], v40 src0_sel:WORD_1
	v_pk_fma_f32 v[236:237], v[128:129], v[250:251], v[236:237] op_sel_hi:[0,1,1]
	v_cvt_pk_f32_fp8_e32 v[250:251], v41
	v_pk_fma_f32 v[238:239], v[128:129], v[250:251], v[238:239] op_sel_hi:[0,1,1]
	v_cvt_pk_f32_fp8_sdwa v[250:251], v41 src0_sel:WORD_1
	v_pk_fma_f32 v[240:241], v[128:129], v[250:251], v[240:241] op_sel_hi:[0,1,1]
	v_cvt_pk_f32_fp8_e32 v[250:251], v42
	v_pk_fma_f32 v[242:243], v[128:129], v[250:251], v[242:243] op_sel_hi:[0,1,1]
	v_cvt_pk_f32_fp8_sdwa v[250:251], v42 src0_sel:WORD_1
	v_pk_fma_f32 v[244:245], v[128:129], v[250:251], v[244:245] op_sel_hi:[0,1,1]
	v_cvt_pk_f32_fp8_e32 v[250:251], v43
	v_pk_fma_f32 v[246:247], v[128:129], v[250:251], v[246:247] op_sel_hi:[0,1,1]
	v_cvt_pk_f32_fp8_sdwa v[250:251], v43 src0_sel:WORD_1
	v_pk_fma_f32 v[248:249], v[128:129], v[250:251], v[248:249] op_sel_hi:[0,1,1]
	s_waitcnt vmcnt(4)
	v_cvt_pk_f32_fp8_e32 v[250:251], v44
	v_and_b32_e32 v128, 0xffff0000, v196
	v_pk_fma_f32 v[146:147], v[128:129], v[250:251], v[146:147] op_sel_hi:[0,1,1]
	v_cvt_pk_f32_fp8_sdwa v[250:251], v44 src0_sel:WORD_1
	v_pk_fma_f32 v[236:237], v[128:129], v[250:251], v[236:237] op_sel_hi:[0,1,1]
	v_cvt_pk_f32_fp8_e32 v[250:251], v45
	v_pk_fma_f32 v[238:239], v[128:129], v[250:251], v[238:239] op_sel_hi:[0,1,1]
	v_cvt_pk_f32_fp8_sdwa v[250:251], v45 src0_sel:WORD_1
	v_pk_fma_f32 v[240:241], v[128:129], v[250:251], v[240:241] op_sel_hi:[0,1,1]
	v_cvt_pk_f32_fp8_e32 v[250:251], v46
	v_pk_fma_f32 v[242:243], v[128:129], v[250:251], v[242:243] op_sel_hi:[0,1,1]
	v_cvt_pk_f32_fp8_sdwa v[250:251], v46 src0_sel:WORD_1
	v_pk_fma_f32 v[244:245], v[128:129], v[250:251], v[244:245] op_sel_hi:[0,1,1]
	v_cvt_pk_f32_fp8_e32 v[250:251], v47
	v_pk_fma_f32 v[246:247], v[128:129], v[250:251], v[246:247] op_sel_hi:[0,1,1]
	v_cvt_pk_f32_fp8_sdwa v[250:251], v47 src0_sel:WORD_1
	v_pk_fma_f32 v[248:249], v[128:129], v[250:251], v[248:249] op_sel_hi:[0,1,1]
	s_waitcnt vmcnt(3)
	v_cvt_pk_f32_fp8_e32 v[250:251], v48
	v_and_b32_e32 v128, 0xffff0000, v215
	v_pk_fma_f32 v[146:147], v[128:129], v[250:251], v[146:147] op_sel_hi:[0,1,1]
	v_cvt_pk_f32_fp8_sdwa v[250:251], v48 src0_sel:WORD_1
	v_pk_fma_f32 v[236:237], v[128:129], v[250:251], v[236:237] op_sel_hi:[0,1,1]
	v_cvt_pk_f32_fp8_e32 v[250:251], v49
	v_pk_fma_f32 v[238:239], v[128:129], v[250:251], v[238:239] op_sel_hi:[0,1,1]
	v_cvt_pk_f32_fp8_sdwa v[250:251], v49 src0_sel:WORD_1
	v_pk_fma_f32 v[240:241], v[128:129], v[250:251], v[240:241] op_sel_hi:[0,1,1]
	v_cvt_pk_f32_fp8_e32 v[250:251], v50
	v_pk_fma_f32 v[242:243], v[128:129], v[250:251], v[242:243] op_sel_hi:[0,1,1]
	v_cvt_pk_f32_fp8_sdwa v[250:251], v50 src0_sel:WORD_1
	v_pk_fma_f32 v[244:245], v[128:129], v[250:251], v[244:245] op_sel_hi:[0,1,1]
	v_cvt_pk_f32_fp8_e32 v[250:251], v51
	v_pk_fma_f32 v[246:247], v[128:129], v[250:251], v[246:247] op_sel_hi:[0,1,1]
	v_cvt_pk_f32_fp8_sdwa v[250:251], v51 src0_sel:WORD_1
	v_pk_fma_f32 v[248:249], v[128:129], v[250:251], v[248:249] op_sel_hi:[0,1,1]
	s_waitcnt vmcnt(2)
	v_cvt_pk_f32_fp8_e32 v[250:251], v52
	v_and_b32_e32 v128, 0xffff0000, v217
	v_pk_fma_f32 v[146:147], v[128:129], v[250:251], v[146:147] op_sel_hi:[0,1,1]
	v_cvt_pk_f32_fp8_sdwa v[250:251], v52 src0_sel:WORD_1
	v_pk_fma_f32 v[236:237], v[128:129], v[250:251], v[236:237] op_sel_hi:[0,1,1]
	v_cvt_pk_f32_fp8_e32 v[250:251], v53
	v_pk_fma_f32 v[238:239], v[128:129], v[250:251], v[238:239] op_sel_hi:[0,1,1]
	v_cvt_pk_f32_fp8_sdwa v[250:251], v53 src0_sel:WORD_1
	v_pk_fma_f32 v[240:241], v[128:129], v[250:251], v[240:241] op_sel_hi:[0,1,1]
	v_cvt_pk_f32_fp8_e32 v[250:251], v54
	v_pk_fma_f32 v[242:243], v[128:129], v[250:251], v[242:243] op_sel_hi:[0,1,1]
	v_cvt_pk_f32_fp8_sdwa v[250:251], v54 src0_sel:WORD_1
	v_pk_fma_f32 v[244:245], v[128:129], v[250:251], v[244:245] op_sel_hi:[0,1,1]
	v_cvt_pk_f32_fp8_e32 v[250:251], v55
	v_pk_fma_f32 v[246:247], v[128:129], v[250:251], v[246:247] op_sel_hi:[0,1,1]
	v_cvt_pk_f32_fp8_sdwa v[250:251], v55 src0_sel:WORD_1
	v_pk_fma_f32 v[248:249], v[128:129], v[250:251], v[248:249] op_sel_hi:[0,1,1]
	s_waitcnt vmcnt(1)
	v_cvt_pk_f32_fp8_e32 v[250:251], v56
	v_and_b32_e32 v128, 0xffff0000, v218
	v_pk_fma_f32 v[146:147], v[128:129], v[250:251], v[146:147] op_sel_hi:[0,1,1]
	v_cvt_pk_f32_fp8_sdwa v[250:251], v56 src0_sel:WORD_1
	v_pk_fma_f32 v[236:237], v[128:129], v[250:251], v[236:237] op_sel_hi:[0,1,1]
	v_cvt_pk_f32_fp8_e32 v[250:251], v57
	v_pk_fma_f32 v[238:239], v[128:129], v[250:251], v[238:239] op_sel_hi:[0,1,1]
	v_cvt_pk_f32_fp8_sdwa v[250:251], v57 src0_sel:WORD_1
	v_pk_fma_f32 v[240:241], v[128:129], v[250:251], v[240:241] op_sel_hi:[0,1,1]
	v_cvt_pk_f32_fp8_e32 v[250:251], v58
	v_pk_fma_f32 v[242:243], v[128:129], v[250:251], v[242:243] op_sel_hi:[0,1,1]
	v_cvt_pk_f32_fp8_sdwa v[250:251], v58 src0_sel:WORD_1
	v_pk_fma_f32 v[244:245], v[128:129], v[250:251], v[244:245] op_sel_hi:[0,1,1]
	v_cvt_pk_f32_fp8_e32 v[250:251], v59
	v_pk_fma_f32 v[246:247], v[128:129], v[250:251], v[246:247] op_sel_hi:[0,1,1]
	v_cvt_pk_f32_fp8_sdwa v[250:251], v59 src0_sel:WORD_1
	v_pk_fma_f32 v[248:249], v[128:129], v[250:251], v[248:249] op_sel_hi:[0,1,1]
	s_waitcnt vmcnt(0)
	v_cvt_pk_f32_fp8_e32 v[250:251], v60
	v_and_b32_e32 v128, 0xffff0000, v219
	v_pk_fma_f32 v[146:147], v[128:129], v[250:251], v[146:147] op_sel_hi:[0,1,1]
	v_cvt_pk_f32_fp8_sdwa v[250:251], v60 src0_sel:WORD_1
	v_pk_fma_f32 v[236:237], v[128:129], v[250:251], v[236:237] op_sel_hi:[0,1,1]
	v_cvt_pk_f32_fp8_e32 v[250:251], v61
	v_pk_fma_f32 v[238:239], v[128:129], v[250:251], v[238:239] op_sel_hi:[0,1,1]
	v_cvt_pk_f32_fp8_sdwa v[250:251], v61 src0_sel:WORD_1
	v_pk_fma_f32 v[240:241], v[128:129], v[250:251], v[240:241] op_sel_hi:[0,1,1]
	v_cvt_pk_f32_fp8_e32 v[250:251], v62
	v_pk_fma_f32 v[242:243], v[128:129], v[250:251], v[242:243] op_sel_hi:[0,1,1]
	v_cvt_pk_f32_fp8_sdwa v[250:251], v62 src0_sel:WORD_1
	v_pk_fma_f32 v[244:245], v[128:129], v[250:251], v[244:245] op_sel_hi:[0,1,1]
	v_cvt_pk_f32_fp8_e32 v[250:251], v63
	v_pk_fma_f32 v[246:247], v[128:129], v[250:251], v[246:247] op_sel_hi:[0,1,1]
	v_cvt_pk_f32_fp8_sdwa v[250:251], v63 src0_sel:WORD_1
	v_pk_fma_f32 v[248:249], v[128:129], v[250:251], v[248:249] op_sel_hi:[0,1,1]
	v_permlane32_swap_b32_e32 v146, v242
	v_permlane32_swap_b32_e32 v147, v243
	v_permlane32_swap_b32_e32 v236, v244
	v_permlane32_swap_b32_e32 v237, v245
	v_permlane32_swap_b32_e32 v238, v246
	v_permlane32_swap_b32_e32 v239, v247
	v_permlane32_swap_b32_e32 v240, v248
	v_permlane32_swap_b32_e32 v241, v249
	v_pk_add_f32 v[146:147], v[146:147], v[242:243]
	v_pk_add_f32 v[236:237], v[236:237], v[244:245]
	v_pk_add_f32 v[238:239], v[238:239], v[246:247]
	v_pk_add_f32 v[240:241], v[240:241], v[248:249]
	s_nop 1
	v_permlane16_swap_b32_e32 v146, v238
	v_permlane16_swap_b32_e32 v147, v239
	v_permlane16_swap_b32_e32 v236, v240
	v_permlane16_swap_b32_e32 v237, v241
	v_pk_add_f32 v[146:147], v[146:147], v[238:239]
	v_pk_add_f32 v[236:237], v[236:237], v[240:241]
	s_nop 1
	v_add_f32_dpp v146, v146, v146 row_ror:8 row_mask:0xf bank_mask:0x3
	v_add_f32_dpp v146, v236, v236 row_ror:8 row_mask:0xf bank_mask:0xc
	v_add_f32_dpp v147, v147, v147 row_ror:8 row_mask:0xf bank_mask:0x3
	v_add_f32_dpp v147, v237, v237 row_ror:8 row_mask:0xf bank_mask:0xc
	s_waitcnt lgkmcnt(0)
	v_lshlrev_b64 v[236:237], 12, v[142:143]
	v_lshl_add_u64 v[236:237], v[134:135], 0, v[236:237]
	v_mov_b32_e32 v139, 0
	s_nop 0
	v_pk_add_f32 v[144:145], v[146:147], v[144:145]
	global_store_dwordx2 v[236:237], v[144:145], off
	v_pk_mul_f32 v[144:145], v[144:145], v[144:145]
	s_nop 0
	v_add_f32_e32 v128, v144, v145
	s_nop 1
	v_add_f32_dpp v128, v128, v128 quad_perm:[1,0,3,2] row_mask:0xf bank_mask:0xf bound_ctrl:1
	s_nop 1
	v_add_f32_dpp v128, v128, v128 quad_perm:[2,3,0,1] row_mask:0xf bank_mask:0xf bound_ctrl:1
	s_nop 1
	v_add_f32_dpp v128, v128, v128 row_half_mirror row_mask:0xf bank_mask:0xf bound_ctrl:1
	s_nop 1
	v_add_f32_dpp v128, v128, v128 row_mirror row_mask:0xf bank_mask:0xf bound_ctrl:1
	s_nop 1
	v_mov_b32_dpp v139, v128 row_bcast:15 row_mask:0xa bank_mask:0xf
	v_add_f32_e32 v128, v128, v139
	v_mov_b32_e32 v139, 0
	s_nop 1
	v_mov_b32_dpp v139, v128 row_bcast:31 row_mask:0xc bank_mask:0xf
	v_add_f32_e32 v128, v128, v139
	s_nop 0
	v_readlane_b32 s28, v128, 63
	s_and_saveexec_b64 s[26:27], s[18:19]
	s_cbranch_execz .LBB0_691
	v_lshl_add_u64 v[144:145], v[142:143], 2, s[30:31]
	v_mov_b32_e32 v128, s28
	global_store_dword v[144:145], v128, off

.LBB0_696:
	s_or_b64 exec, exec, s[22:23]
	v_cvt_pk_f32_fp8_e32 v[142:143], v68
	v_cvt_pk_f32_fp8_sdwa v[144:145], v68 src0_sel:WORD_1
	v_cvt_pk_f32_fp8_e32 v[236:237], v69
	v_cvt_pk_f32_fp8_sdwa v[238:239], v69 src0_sel:WORD_1
	v_cvt_pk_f32_fp8_e32 v[240:241], v70
	v_cvt_pk_f32_fp8_sdwa v[242:243], v70 src0_sel:WORD_1
	v_cvt_pk_f32_fp8_e32 v[244:245], v71
	v_cvt_pk_f32_fp8_sdwa v[246:247], v71 src0_sel:WORD_1
	v_cvt_pk_f32_fp8_e32 v[248:249], v64
	v_and_b32_e32 v128, 0xffff0000, v220
	v_pk_fma_f32 v[142:143], v[128:129], v[142:143], 0 op_sel_hi:[0,1,0]
	v_pk_fma_f32 v[144:145], v[128:129], v[144:145], 0 op_sel_hi:[0,1,0]
	v_pk_fma_f32 v[236:237], v[128:129], v[236:237], 0 op_sel_hi:[0,1,0]
	v_pk_fma_f32 v[238:239], v[128:129], v[238:239], 0 op_sel_hi:[0,1,0]
	v_pk_fma_f32 v[240:241], v[128:129], v[240:241], 0 op_sel_hi:[0,1,0]
	v_pk_fma_f32 v[242:243], v[128:129], v[242:243], 0 op_sel_hi:[0,1,0]
	v_pk_fma_f32 v[244:245], v[128:129], v[244:245], 0 op_sel_hi:[0,1,0]
	v_pk_fma_f32 v[246:247], v[128:129], v[246:247], 0 op_sel_hi:[0,1,0]
	v_and_b32_e32 v128, 0xffff0000, v221
	v_pk_fma_f32 v[142:143], v[128:129], v[248:249], v[142:143] op_sel_hi:[0,1,1]
	v_cvt_pk_f32_fp8_sdwa v[248:249], v64 src0_sel:WORD_1
	v_pk_fma_f32 v[144:145], v[128:129], v[248:249], v[144:145] op_sel_hi:[0,1,1]
	v_cvt_pk_f32_fp8_e32 v[248:249], v65
	v_pk_fma_f32 v[236:237], v[128:129], v[248:249], v[236:237] op_sel_hi:[0,1,1]
	v_cvt_pk_f32_fp8_sdwa v[248:249], v65 src0_sel:WORD_1
	v_pk_fma_f32 v[238:239], v[128:129], v[248:249], v[238:239] op_sel_hi:[0,1,1]
	v_cvt_pk_f32_fp8_e32 v[248:249], v66
	v_pk_fma_f32 v[240:241], v[128:129], v[248:249], v[240:241] op_sel_hi:[0,1,1]
	v_cvt_pk_f32_fp8_sdwa v[248:249], v66 src0_sel:WORD_1
	v_pk_fma_f32 v[242:243], v[128:129], v[248:249], v[242:243] op_sel_hi:[0,1,1]
	v_cvt_pk_f32_fp8_e32 v[248:249], v67
	v_pk_fma_f32 v[244:245], v[128:129], v[248:249], v[244:245] op_sel_hi:[0,1,1]
	v_cvt_pk_f32_fp8_sdwa v[248:249], v67 src0_sel:WORD_1
	v_pk_fma_f32 v[246:247], v[128:129], v[248:249], v[246:247] op_sel_hi:[0,1,1]
	v_cvt_pk_f32_fp8_e32 v[248:249], v76
	v_and_b32_e32 v128, 0xffff0000, v222
	v_pk_fma_f32 v[142:143], v[128:129], v[248:249], v[142:143] op_sel_hi:[0,1,1]
	v_cvt_pk_f32_fp8_sdwa v[248:249], v76 src0_sel:WORD_1
	v_pk_fma_f32 v[144:145], v[128:129], v[248:249], v[144:145] op_sel_hi:[0,1,1]
	v_cvt_pk_f32_fp8_e32 v[248:249], v77
	v_pk_fma_f32 v[236:237], v[128:129], v[248:249], v[236:237] op_sel_hi:[0,1,1]
	v_cvt_pk_f32_fp8_sdwa v[248:249], v77 src0_sel:WORD_1
	v_pk_fma_f32 v[238:239], v[128:129], v[248:249], v[238:239] op_sel_hi:[0,1,1]
	v_cvt_pk_f32_fp8_e32 v[248:249], v78
	v_pk_fma_f32 v[240:241], v[128:129], v[248:249], v[240:241] op_sel_hi:[0,1,1]
	v_cvt_pk_f32_fp8_sdwa v[248:249], v78 src0_sel:WORD_1
	v_pk_fma_f32 v[242:243], v[128:129], v[248:249], v[242:243] op_sel_hi:[0,1,1]
	v_cvt_pk_f32_fp8_e32 v[248:249], v79
	v_pk_fma_f32 v[244:245], v[128:129], v[248:249], v[244:245] op_sel_hi:[0,1,1]
	v_cvt_pk_f32_fp8_sdwa v[248:249], v79 src0_sel:WORD_1
	v_pk_fma_f32 v[246:247], v[128:129], v[248:249], v[246:247] op_sel_hi:[0,1,1]
	v_cvt_pk_f32_fp8_e32 v[248:249], v72
	v_and_b32_e32 v128, 0xffff0000, v223
	v_pk_fma_f32 v[142:143], v[128:129], v[248:249], v[142:143] op_sel_hi:[0,1,1]
	v_cvt_pk_f32_fp8_sdwa v[248:249], v72 src0_sel:WORD_1
	v_pk_fma_f32 v[144:145], v[128:129], v[248:249], v[144:145] op_sel_hi:[0,1,1]
	v_cvt_pk_f32_fp8_e32 v[248:249], v73
	v_pk_fma_f32 v[236:237], v[128:129], v[248:249], v[236:237] op_sel_hi:[0,1,1]
	v_cvt_pk_f32_fp8_sdwa v[248:249], v73 src0_sel:WORD_1
	v_pk_fma_f32 v[238:239], v[128:129], v[248:249], v[238:239] op_sel_hi:[0,1,1]
	v_cvt_pk_f32_fp8_e32 v[248:249], v74
	v_pk_fma_f32 v[240:241], v[128:129], v[248:249], v[240:241] op_sel_hi:[0,1,1]
	v_cvt_pk_f32_fp8_sdwa v[248:249], v74 src0_sel:WORD_1
	v_pk_fma_f32 v[242:243], v[128:129], v[248:249], v[242:243] op_sel_hi:[0,1,1]
	v_cvt_pk_f32_fp8_e32 v[248:249], v75
	v_pk_fma_f32 v[244:245], v[128:129], v[248:249], v[244:245] op_sel_hi:[0,1,1]
	v_cvt_pk_f32_fp8_sdwa v[248:249], v75 src0_sel:WORD_1
	v_pk_fma_f32 v[246:247], v[128:129], v[248:249], v[246:247] op_sel_hi:[0,1,1]
	v_cvt_pk_f32_fp8_e32 v[248:249], v84
	v_and_b32_e32 v128, 0xffff0000, v224
	v_pk_fma_f32 v[142:143], v[128:129], v[248:249], v[142:143] op_sel_hi:[0,1,1]
	v_cvt_pk_f32_fp8_sdwa v[248:249], v84 src0_sel:WORD_1
	v_pk_fma_f32 v[144:145], v[128:129], v[248:249], v[144:145] op_sel_hi:[0,1,1]
	v_cvt_pk_f32_fp8_e32 v[248:249], v85
	v_pk_fma_f32 v[236:237], v[128:129], v[248:249], v[236:237] op_sel_hi:[0,1,1]
	v_cvt_pk_f32_fp8_sdwa v[248:249], v85 src0_sel:WORD_1
	v_pk_fma_f32 v[238:239], v[128:129], v[248:249], v[238:239] op_sel_hi:[0,1,1]
	v_cvt_pk_f32_fp8_e32 v[248:249], v86
	v_pk_fma_f32 v[240:241], v[128:129], v[248:249], v[240:241] op_sel_hi:[0,1,1]
	v_cvt_pk_f32_fp8_sdwa v[248:249], v86 src0_sel:WORD_1
	v_pk_fma_f32 v[242:243], v[128:129], v[248:249], v[242:243] op_sel_hi:[0,1,1]
	v_cvt_pk_f32_fp8_e32 v[248:249], v87
	v_pk_fma_f32 v[244:245], v[128:129], v[248:249], v[244:245] op_sel_hi:[0,1,1]
	v_cvt_pk_f32_fp8_sdwa v[248:249], v87 src0_sel:WORD_1
	v_pk_fma_f32 v[246:247], v[128:129], v[248:249], v[246:247] op_sel_hi:[0,1,1]
	v_cvt_pk_f32_fp8_e32 v[248:249], v80
	v_and_b32_e32 v128, 0xffff0000, v225
	v_pk_fma_f32 v[142:143], v[128:129], v[248:249], v[142:143] op_sel_hi:[0,1,1]
	v_cvt_pk_f32_fp8_sdwa v[248:249], v80 src0_sel:WORD_1
	v_pk_fma_f32 v[144:145], v[128:129], v[248:249], v[144:145] op_sel_hi:[0,1,1]
	v_cvt_pk_f32_fp8_e32 v[248:249], v81
	v_pk_fma_f32 v[236:237], v[128:129], v[248:249], v[236:237] op_sel_hi:[0,1,1]
	v_cvt_pk_f32_fp8_sdwa v[248:249], v81 src0_sel:WORD_1
	v_pk_fma_f32 v[238:239], v[128:129], v[248:249], v[238:239] op_sel_hi:[0,1,1]
	v_cvt_pk_f32_fp8_e32 v[248:249], v82
	v_pk_fma_f32 v[240:241], v[128:129], v[248:249], v[240:241] op_sel_hi:[0,1,1]
	v_cvt_pk_f32_fp8_sdwa v[248:249], v82 src0_sel:WORD_1
	v_pk_fma_f32 v[242:243], v[128:129], v[248:249], v[242:243] op_sel_hi:[0,1,1]
	v_cvt_pk_f32_fp8_e32 v[248:249], v83
	v_pk_fma_f32 v[244:245], v[128:129], v[248:249], v[244:245] op_sel_hi:[0,1,1]
	v_cvt_pk_f32_fp8_sdwa v[248:249], v83 src0_sel:WORD_1
	v_pk_fma_f32 v[246:247], v[128:129], v[248:249], v[246:247] op_sel_hi:[0,1,1]
	v_cvt_pk_f32_fp8_e32 v[248:249], v92
	v_and_b32_e32 v128, 0xffff0000, v226
	v_pk_fma_f32 v[142:143], v[128:129], v[248:249], v[142:143] op_sel_hi:[0,1,1]
	v_cvt_pk_f32_fp8_sdwa v[248:249], v92 src0_sel:WORD_1
	v_pk_fma_f32 v[144:145], v[128:129], v[248:249], v[144:145] op_sel_hi:[0,1,1]
	v_cvt_pk_f32_fp8_e32 v[248:249], v93
	v_pk_fma_f32 v[236:237], v[128:129], v[248:249], v[236:237] op_sel_hi:[0,1,1]
	v_cvt_pk_f32_fp8_sdwa v[248:249], v93 src0_sel:WORD_1
	v_pk_fma_f32 v[238:239], v[128:129], v[248:249], v[238:239] op_sel_hi:[0,1,1]
	v_cvt_pk_f32_fp8_e32 v[248:249], v94
	v_pk_fma_f32 v[240:241], v[128:129], v[248:249], v[240:241] op_sel_hi:[0,1,1]
	v_cvt_pk_f32_fp8_sdwa v[248:249], v94 src0_sel:WORD_1
	v_pk_fma_f32 v[242:243], v[128:129], v[248:249], v[242:243] op_sel_hi:[0,1,1]
	v_cvt_pk_f32_fp8_e32 v[248:249], v95
	v_pk_fma_f32 v[244:245], v[128:129], v[248:249], v[244:245] op_sel_hi:[0,1,1]
	v_cvt_pk_f32_fp8_sdwa v[248:249], v95 src0_sel:WORD_1
	v_pk_fma_f32 v[246:247], v[128:129], v[248:249], v[246:247] op_sel_hi:[0,1,1]
	v_cvt_pk_f32_fp8_e32 v[248:249], v88
	v_and_b32_e32 v128, 0xffff0000, v227
	v_pk_fma_f32 v[142:143], v[128:129], v[248:249], v[142:143] op_sel_hi:[0,1,1]
	v_cvt_pk_f32_fp8_sdwa v[248:249], v88 src0_sel:WORD_1
	v_pk_fma_f32 v[144:145], v[128:129], v[248:249], v[144:145] op_sel_hi:[0,1,1]
	v_cvt_pk_f32_fp8_e32 v[248:249], v89
	v_pk_fma_f32 v[236:237], v[128:129], v[248:249], v[236:237] op_sel_hi:[0,1,1]
	v_cvt_pk_f32_fp8_sdwa v[248:249], v89 src0_sel:WORD_1
	v_pk_fma_f32 v[238:239], v[128:129], v[248:249], v[238:239] op_sel_hi:[0,1,1]
	v_cvt_pk_f32_fp8_e32 v[248:249], v90
	v_pk_fma_f32 v[240:241], v[128:129], v[248:249], v[240:241] op_sel_hi:[0,1,1]
	v_cvt_pk_f32_fp8_sdwa v[248:249], v90 src0_sel:WORD_1
	v_pk_fma_f32 v[242:243], v[128:129], v[248:249], v[242:243] op_sel_hi:[0,1,1]
	v_cvt_pk_f32_fp8_e32 v[248:249], v91
	v_pk_fma_f32 v[244:245], v[128:129], v[248:249], v[244:245] op_sel_hi:[0,1,1]
	v_cvt_pk_f32_fp8_sdwa v[248:249], v91 src0_sel:WORD_1
	v_pk_fma_f32 v[246:247], v[128:129], v[248:249], v[246:247] op_sel_hi:[0,1,1]
	v_cvt_pk_f32_fp8_e32 v[248:249], v100
	v_and_b32_e32 v128, 0xffff0000, v228
	v_pk_fma_f32 v[142:143], v[128:129], v[248:249], v[142:143] op_sel_hi:[0,1,1]
	v_cvt_pk_f32_fp8_sdwa v[248:249], v100 src0_sel:WORD_1
	v_pk_fma_f32 v[144:145], v[128:129], v[248:249], v[144:145] op_sel_hi:[0,1,1]
	v_cvt_pk_f32_fp8_e32 v[248:249], v101
	v_pk_fma_f32 v[236:237], v[128:129], v[248:249], v[236:237] op_sel_hi:[0,1,1]
	v_cvt_pk_f32_fp8_sdwa v[248:249], v101 src0_sel:WORD_1
	v_pk_fma_f32 v[238:239], v[128:129], v[248:249], v[238:239] op_sel_hi:[0,1,1]
	v_cvt_pk_f32_fp8_e32 v[248:249], v102
	v_pk_fma_f32 v[240:241], v[128:129], v[248:249], v[240:241] op_sel_hi:[0,1,1]
	v_cvt_pk_f32_fp8_sdwa v[248:249], v102 src0_sel:WORD_1
	v_pk_fma_f32 v[242:243], v[128:129], v[248:249], v[242:243] op_sel_hi:[0,1,1]
	v_cvt_pk_f32_fp8_e32 v[248:249], v103
	v_pk_fma_f32 v[244:245], v[128:129], v[248:249], v[244:245] op_sel_hi:[0,1,1]
	v_cvt_pk_f32_fp8_sdwa v[248:249], v103 src0_sel:WORD_1
	v_pk_fma_f32 v[246:247], v[128:129], v[248:249], v[246:247] op_sel_hi:[0,1,1]
	v_cvt_pk_f32_fp8_e32 v[248:249], v96
	v_and_b32_e32 v128, 0xffff0000, v229
	v_pk_fma_f32 v[142:143], v[128:129], v[248:249], v[142:143] op_sel_hi:[0,1,1]
	v_cvt_pk_f32_fp8_sdwa v[248:249], v96 src0_sel:WORD_1
	v_pk_fma_f32 v[144:145], v[128:129], v[248:249], v[144:145] op_sel_hi:[0,1,1]
	v_cvt_pk_f32_fp8_e32 v[248:249], v97
	v_pk_fma_f32 v[236:237], v[128:129], v[248:249], v[236:237] op_sel_hi:[0,1,1]
	v_cvt_pk_f32_fp8_sdwa v[248:249], v97 src0_sel:WORD_1
	v_pk_fma_f32 v[238:239], v[128:129], v[248:249], v[238:239] op_sel_hi:[0,1,1]
	v_cvt_pk_f32_fp8_e32 v[248:249], v98
	v_pk_fma_f32 v[240:241], v[128:129], v[248:249], v[240:241] op_sel_hi:[0,1,1]
	v_cvt_pk_f32_fp8_sdwa v[248:249], v98 src0_sel:WORD_1
	v_pk_fma_f32 v[242:243], v[128:129], v[248:249], v[242:243] op_sel_hi:[0,1,1]
	v_cvt_pk_f32_fp8_e32 v[248:249], v99
	v_pk_fma_f32 v[244:245], v[128:129], v[248:249], v[244:245] op_sel_hi:[0,1,1]
	v_cvt_pk_f32_fp8_sdwa v[248:249], v99 src0_sel:WORD_1
	v_pk_fma_f32 v[246:247], v[128:129], v[248:249], v[246:247] op_sel_hi:[0,1,1]
	v_cvt_pk_f32_fp8_e32 v[248:249], v108
	v_and_b32_e32 v128, 0xffff0000, v230
	v_pk_fma_f32 v[142:143], v[128:129], v[248:249], v[142:143] op_sel_hi:[0,1,1]
	v_cvt_pk_f32_fp8_sdwa v[248:249], v108 src0_sel:WORD_1
	v_pk_fma_f32 v[144:145], v[128:129], v[248:249], v[144:145] op_sel_hi:[0,1,1]
	v_cvt_pk_f32_fp8_e32 v[248:249], v109
	v_pk_fma_f32 v[236:237], v[128:129], v[248:249], v[236:237] op_sel_hi:[0,1,1]
	v_cvt_pk_f32_fp8_sdwa v[248:249], v109 src0_sel:WORD_1
	v_pk_fma_f32 v[238:239], v[128:129], v[248:249], v[238:239] op_sel_hi:[0,1,1]
	v_cvt_pk_f32_fp8_e32 v[248:249], v110
	v_pk_fma_f32 v[240:241], v[128:129], v[248:249], v[240:241] op_sel_hi:[0,1,1]
	v_cvt_pk_f32_fp8_sdwa v[248:249], v110 src0_sel:WORD_1
	v_pk_fma_f32 v[242:243], v[128:129], v[248:249], v[242:243] op_sel_hi:[0,1,1]
	v_cvt_pk_f32_fp8_e32 v[248:249], v111
	v_pk_fma_f32 v[244:245], v[128:129], v[248:249], v[244:245] op_sel_hi:[0,1,1]
	v_cvt_pk_f32_fp8_sdwa v[248:249], v111 src0_sel:WORD_1
	v_pk_fma_f32 v[246:247], v[128:129], v[248:249], v[246:247] op_sel_hi:[0,1,1]
	v_cvt_pk_f32_fp8_e32 v[248:249], v104
	v_and_b32_e32 v128, 0xffff0000, v231
	v_pk_fma_f32 v[142:143], v[128:129], v[248:249], v[142:143] op_sel_hi:[0,1,1]
	v_cvt_pk_f32_fp8_sdwa v[248:249], v104 src0_sel:WORD_1
	v_pk_fma_f32 v[144:145], v[128:129], v[248:249], v[144:145] op_sel_hi:[0,1,1]
	v_cvt_pk_f32_fp8_e32 v[248:249], v105
	v_pk_fma_f32 v[236:237], v[128:129], v[248:249], v[236:237] op_sel_hi:[0,1,1]
	v_cvt_pk_f32_fp8_sdwa v[248:249], v105 src0_sel:WORD_1
	v_pk_fma_f32 v[238:239], v[128:129], v[248:249], v[238:239] op_sel_hi:[0,1,1]
	v_cvt_pk_f32_fp8_e32 v[248:249], v106
	v_pk_fma_f32 v[240:241], v[128:129], v[248:249], v[240:241] op_sel_hi:[0,1,1]
	v_cvt_pk_f32_fp8_sdwa v[248:249], v106 src0_sel:WORD_1
	v_pk_fma_f32 v[242:243], v[128:129], v[248:249], v[242:243] op_sel_hi:[0,1,1]
	v_cvt_pk_f32_fp8_e32 v[248:249], v107
	v_pk_fma_f32 v[244:245], v[128:129], v[248:249], v[244:245] op_sel_hi:[0,1,1]
	v_cvt_pk_f32_fp8_sdwa v[248:249], v107 src0_sel:WORD_1
	v_pk_fma_f32 v[246:247], v[128:129], v[248:249], v[246:247] op_sel_hi:[0,1,1]
	v_cvt_pk_f32_fp8_e32 v[248:249], v116
	v_and_b32_e32 v128, 0xffff0000, v232
	v_pk_fma_f32 v[142:143], v[128:129], v[248:249], v[142:143] op_sel_hi:[0,1,1]
	v_cvt_pk_f32_fp8_sdwa v[248:249], v116 src0_sel:WORD_1
	v_pk_fma_f32 v[144:145], v[128:129], v[248:249], v[144:145] op_sel_hi:[0,1,1]
	v_cvt_pk_f32_fp8_e32 v[248:249], v117
	v_pk_fma_f32 v[236:237], v[128:129], v[248:249], v[236:237] op_sel_hi:[0,1,1]
	v_cvt_pk_f32_fp8_sdwa v[248:249], v117 src0_sel:WORD_1
	v_pk_fma_f32 v[238:239], v[128:129], v[248:249], v[238:239] op_sel_hi:[0,1,1]
	v_cvt_pk_f32_fp8_e32 v[248:249], v118
	v_pk_fma_f32 v[240:241], v[128:129], v[248:249], v[240:241] op_sel_hi:[0,1,1]
	v_cvt_pk_f32_fp8_sdwa v[248:249], v118 src0_sel:WORD_1
	v_pk_fma_f32 v[242:243], v[128:129], v[248:249], v[242:243] op_sel_hi:[0,1,1]
	v_cvt_pk_f32_fp8_e32 v[248:249], v119
	v_pk_fma_f32 v[244:245], v[128:129], v[248:249], v[244:245] op_sel_hi:[0,1,1]
	v_cvt_pk_f32_fp8_sdwa v[248:249], v119 src0_sel:WORD_1
	v_pk_fma_f32 v[246:247], v[128:129], v[248:249], v[246:247] op_sel_hi:[0,1,1]
	v_cvt_pk_f32_fp8_e32 v[248:249], v112
	v_and_b32_e32 v128, 0xffff0000, v233
	v_pk_fma_f32 v[142:143], v[128:129], v[248:249], v[142:143] op_sel_hi:[0,1,1]
	v_cvt_pk_f32_fp8_sdwa v[248:249], v112 src0_sel:WORD_1
	v_pk_fma_f32 v[144:145], v[128:129], v[248:249], v[144:145] op_sel_hi:[0,1,1]
	v_cvt_pk_f32_fp8_e32 v[248:249], v113
	v_pk_fma_f32 v[236:237], v[128:129], v[248:249], v[236:237] op_sel_hi:[0,1,1]
	v_cvt_pk_f32_fp8_sdwa v[248:249], v113 src0_sel:WORD_1
	v_pk_fma_f32 v[238:239], v[128:129], v[248:249], v[238:239] op_sel_hi:[0,1,1]
	v_cvt_pk_f32_fp8_e32 v[248:249], v114
	v_pk_fma_f32 v[240:241], v[128:129], v[248:249], v[240:241] op_sel_hi:[0,1,1]
	v_cvt_pk_f32_fp8_sdwa v[248:249], v114 src0_sel:WORD_1
	v_pk_fma_f32 v[242:243], v[128:129], v[248:249], v[242:243] op_sel_hi:[0,1,1]
	v_cvt_pk_f32_fp8_e32 v[248:249], v115
	v_pk_fma_f32 v[244:245], v[128:129], v[248:249], v[244:245] op_sel_hi:[0,1,1]
	v_cvt_pk_f32_fp8_sdwa v[248:249], v115 src0_sel:WORD_1
	v_pk_fma_f32 v[246:247], v[128:129], v[248:249], v[246:247] op_sel_hi:[0,1,1]
	v_cvt_pk_f32_fp8_e32 v[248:249], v124
	v_and_b32_e32 v128, 0xffff0000, v234
	v_pk_fma_f32 v[142:143], v[128:129], v[248:249], v[142:143] op_sel_hi:[0,1,1]
	v_cvt_pk_f32_fp8_sdwa v[248:249], v124 src0_sel:WORD_1
	v_pk_fma_f32 v[144:145], v[128:129], v[248:249], v[144:145] op_sel_hi:[0,1,1]
	v_cvt_pk_f32_fp8_e32 v[248:249], v125
	v_pk_fma_f32 v[236:237], v[128:129], v[248:249], v[236:237] op_sel_hi:[0,1,1]
	v_cvt_pk_f32_fp8_sdwa v[248:249], v125 src0_sel:WORD_1
	v_pk_fma_f32 v[238:239], v[128:129], v[248:249], v[238:239] op_sel_hi:[0,1,1]
	v_cvt_pk_f32_fp8_e32 v[248:249], v126
	v_pk_fma_f32 v[240:241], v[128:129], v[248:249], v[240:241] op_sel_hi:[0,1,1]
	v_cvt_pk_f32_fp8_sdwa v[248:249], v126 src0_sel:WORD_1
	v_pk_fma_f32 v[242:243], v[128:129], v[248:249], v[242:243] op_sel_hi:[0,1,1]
	v_cvt_pk_f32_fp8_e32 v[248:249], v127
	v_pk_fma_f32 v[244:245], v[128:129], v[248:249], v[244:245] op_sel_hi:[0,1,1]
	v_cvt_pk_f32_fp8_sdwa v[248:249], v127 src0_sel:WORD_1
	v_pk_fma_f32 v[246:247], v[128:129], v[248:249], v[246:247] op_sel_hi:[0,1,1]
	v_cvt_pk_f32_fp8_e32 v[248:249], v120
	v_and_b32_e32 v128, 0xffff0000, v235
	v_pk_fma_f32 v[142:143], v[128:129], v[248:249], v[142:143] op_sel_hi:[0,1,1]
	v_cvt_pk_f32_fp8_sdwa v[248:249], v120 src0_sel:WORD_1
	v_pk_fma_f32 v[144:145], v[128:129], v[248:249], v[144:145] op_sel_hi:[0,1,1]
	v_cvt_pk_f32_fp8_e32 v[248:249], v121
	v_pk_fma_f32 v[236:237], v[128:129], v[248:249], v[236:237] op_sel_hi:[0,1,1]
	v_cvt_pk_f32_fp8_sdwa v[248:249], v121 src0_sel:WORD_1
	v_pk_fma_f32 v[238:239], v[128:129], v[248:249], v[238:239] op_sel_hi:[0,1,1]
	v_cvt_pk_f32_fp8_e32 v[248:249], v122
	v_pk_fma_f32 v[240:241], v[128:129], v[248:249], v[240:241] op_sel_hi:[0,1,1]
	v_cvt_pk_f32_fp8_sdwa v[248:249], v122 src0_sel:WORD_1
	v_pk_fma_f32 v[242:243], v[128:129], v[248:249], v[242:243] op_sel_hi:[0,1,1]
	v_cvt_pk_f32_fp8_e32 v[248:249], v123
	v_pk_fma_f32 v[244:245], v[128:129], v[248:249], v[244:245] op_sel_hi:[0,1,1]
	v_cvt_pk_f32_fp8_sdwa v[248:249], v123 src0_sel:WORD_1
	v_pk_fma_f32 v[246:247], v[128:129], v[248:249], v[246:247] op_sel_hi:[0,1,1]
	v_permlane32_swap_b32_e32 v142, v240
	v_permlane32_swap_b32_e32 v143, v241
	v_permlane32_swap_b32_e32 v144, v242
	v_permlane32_swap_b32_e32 v145, v243
	v_permlane32_swap_b32_e32 v236, v244
	v_permlane32_swap_b32_e32 v237, v245
	v_permlane32_swap_b32_e32 v238, v246
	v_permlane32_swap_b32_e32 v239, v247
	v_pk_add_f32 v[142:143], v[142:143], v[240:241]
	v_pk_add_f32 v[144:145], v[144:145], v[242:243]
	v_pk_add_f32 v[236:237], v[236:237], v[244:245]
	v_pk_add_f32 v[238:239], v[238:239], v[246:247]
	s_nop 1
	v_permlane16_swap_b32_e32 v142, v236
	v_permlane16_swap_b32_e32 v143, v237
	v_permlane16_swap_b32_e32 v144, v238
	v_permlane16_swap_b32_e32 v145, v239
	v_pk_add_f32 v[142:143], v[142:143], v[236:237]
	v_pk_add_f32 v[144:145], v[144:145], v[238:239]
	s_nop 1
	v_add_f32_dpp v142, v142, v142 row_ror:8 row_mask:0xf bank_mask:0x3
	v_add_f32_dpp v142, v144, v144 row_ror:8 row_mask:0xf bank_mask:0xc
	v_add_f32_dpp v143, v143, v143 row_ror:8 row_mask:0xf bank_mask:0x3
	v_add_f32_dpp v143, v145, v145 row_ror:8 row_mask:0xf bank_mask:0xc
	s_waitcnt lgkmcnt(0)
	v_ashrrev_i32_e32 v139, 31, v138
	v_lshlrev_b64 v[144:145], 12, v[138:139]
	v_lshl_add_u64 v[144:145], v[134:135], 0, v[144:145]
	s_nop 0
	v_pk_add_f32 v[136:137], v[142:143], v[136:137]
	global_store_dwordx2 v[144:145], v[136:137], off
	v_pk_mul_f32 v[136:137], v[136:137], v[136:137]
	s_nop 0
	v_add_f32_e32 v128, v136, v137
	v_mov_b32_e32 v136, 0
	s_nop 0
	v_add_f32_dpp v128, v128, v128 quad_perm:[1,0,3,2] row_mask:0xf bank_mask:0xf bound_ctrl:1
	s_nop 1
	v_add_f32_dpp v128, v128, v128 quad_perm:[2,3,0,1] row_mask:0xf bank_mask:0xf bound_ctrl:1
	s_nop 1
	v_add_f32_dpp v128, v128, v128 row_half_mirror row_mask:0xf bank_mask:0xf bound_ctrl:1
	s_nop 1
	v_add_f32_dpp v128, v128, v128 row_mirror row_mask:0xf bank_mask:0xf bound_ctrl:1
	s_nop 1
	v_mov_b32_dpp v136, v128 row_bcast:15 row_mask:0xa bank_mask:0xf
	v_add_f32_e32 v128, v128, v136
	v_mov_b32_e32 v136, 0
	s_nop 1
	v_mov_b32_dpp v136, v128 row_bcast:31 row_mask:0xc bank_mask:0xf
	v_add_f32_e32 v128, v128, v136
	s_nop 0
	v_readlane_b32 s22, v128, 63
	s_and_saveexec_b64 s[20:21], s[18:19]
	s_cbranch_execz .LBB0_683
	v_lshl_add_u64 v[136:137], v[138:139], 2, s[30:31]
	v_mov_b32_e32 v128, s22
	global_store_dword v[136:137], v128, off
	s_branch .LBB0_683

.LBB0_1151:
	s_or_b64 exec, exec, s[14:15]
	s_waitcnt vmcnt(15)
	v_cvt_pk_f32_fp8_e32 v[206:207], v0
	v_cvt_pk_f32_fp8_sdwa v[208:209], v0 src0_sel:WORD_1
	v_cvt_pk_f32_fp8_e32 v[210:211], v1
	v_cvt_pk_f32_fp8_sdwa v[212:213], v1 src0_sel:WORD_1
	v_cvt_pk_f32_fp8_e32 v[214:215], v2
	v_cvt_pk_f32_fp8_sdwa v[216:217], v2 src0_sel:WORD_1
	v_cvt_pk_f32_fp8_e32 v[218:219], v3
	v_cvt_pk_f32_fp8_sdwa v[220:221], v3 src0_sel:WORD_1
	v_and_b32_e32 v142, 0xffff0000, v149
	v_pk_fma_f32 v[206:207], v[142:143], v[206:207], 0 op_sel_hi:[0,1,0]
	v_pk_fma_f32 v[208:209], v[142:143], v[208:209], 0 op_sel_hi:[0,1,0]
	v_pk_fma_f32 v[210:211], v[142:143], v[210:211], 0 op_sel_hi:[0,1,0]
	v_pk_fma_f32 v[212:213], v[142:143], v[212:213], 0 op_sel_hi:[0,1,0]
	v_pk_fma_f32 v[214:215], v[142:143], v[214:215], 0 op_sel_hi:[0,1,0]
	v_pk_fma_f32 v[216:217], v[142:143], v[216:217], 0 op_sel_hi:[0,1,0]
	v_pk_fma_f32 v[218:219], v[142:143], v[218:219], 0 op_sel_hi:[0,1,0]
	v_pk_fma_f32 v[142:143], v[142:143], v[220:221], 0 op_sel_hi:[0,1,0]
	s_waitcnt vmcnt(14)
	v_cvt_pk_f32_fp8_e32 v[220:221], v4
	v_cvt_pk_f32_fp8_sdwa v[222:223], v4 src0_sel:WORD_1
	v_cvt_pk_f32_fp8_e32 v[224:225], v5
	v_cvt_pk_f32_fp8_sdwa v[226:227], v5 src0_sel:WORD_1
	v_and_b32_e32 v172, 0xffff0000, v150
	v_pk_fma_f32 v[206:207], v[172:173], v[220:221], v[206:207] op_sel_hi:[0,1,1]
	v_cvt_pk_f32_fp8_e32 v[220:221], v6
	v_pk_fma_f32 v[208:209], v[172:173], v[222:223], v[208:209] op_sel_hi:[0,1,1]
	v_pk_fma_f32 v[210:211], v[172:173], v[224:225], v[210:211] op_sel_hi:[0,1,1]
	v_pk_fma_f32 v[212:213], v[172:173], v[226:227], v[212:213] op_sel_hi:[0,1,1]
	v_cvt_pk_f32_fp8_sdwa v[222:223], v6 src0_sel:WORD_1
	v_cvt_pk_f32_fp8_e32 v[224:225], v7
	v_cvt_pk_f32_fp8_sdwa v[226:227], v7 src0_sel:WORD_1
	v_pk_fma_f32 v[214:215], v[172:173], v[220:221], v[214:215] op_sel_hi:[0,1,1]
	s_waitcnt vmcnt(13)
	v_cvt_pk_f32_fp8_e32 v[220:221], v8
	v_pk_fma_f32 v[216:217], v[172:173], v[222:223], v[216:217] op_sel_hi:[0,1,1]
	v_pk_fma_f32 v[218:219], v[172:173], v[224:225], v[218:219] op_sel_hi:[0,1,1]
	v_pk_fma_f32 v[142:143], v[172:173], v[226:227], v[142:143] op_sel_hi:[0,1,1]
	v_cvt_pk_f32_fp8_sdwa v[222:223], v8 src0_sel:WORD_1
	v_cvt_pk_f32_fp8_e32 v[224:225], v9
	v_cvt_pk_f32_fp8_sdwa v[226:227], v9 src0_sel:WORD_1
	v_and_b32_e32 v172, 0xffff0000, v151
	v_pk_fma_f32 v[206:207], v[172:173], v[220:221], v[206:207] op_sel_hi:[0,1,1]
	v_cvt_pk_f32_fp8_e32 v[220:221], v10
	v_pk_fma_f32 v[208:209], v[172:173], v[222:223], v[208:209] op_sel_hi:[0,1,1]
	v_pk_fma_f32 v[210:211], v[172:173], v[224:225], v[210:211] op_sel_hi:[0,1,1]
	v_pk_fma_f32 v[212:213], v[172:173], v[226:227], v[212:213] op_sel_hi:[0,1,1]
	v_cvt_pk_f32_fp8_sdwa v[222:223], v10 src0_sel:WORD_1
	v_cvt_pk_f32_fp8_e32 v[224:225], v11
	v_cvt_pk_f32_fp8_sdwa v[226:227], v11 src0_sel:WORD_1
	v_pk_fma_f32 v[214:215], v[172:173], v[220:221], v[214:215] op_sel_hi:[0,1,1]
	s_waitcnt vmcnt(12)
	v_cvt_pk_f32_fp8_e32 v[220:221], v12
	v_pk_fma_f32 v[216:217], v[172:173], v[222:223], v[216:217] op_sel_hi:[0,1,1]
	v_pk_fma_f32 v[218:219], v[172:173], v[224:225], v[218:219] op_sel_hi:[0,1,1]
	v_pk_fma_f32 v[142:143], v[172:173], v[226:227], v[142:143] op_sel_hi:[0,1,1]
	v_cvt_pk_f32_fp8_sdwa v[222:223], v12 src0_sel:WORD_1
	v_cvt_pk_f32_fp8_e32 v[224:225], v13
	v_cvt_pk_f32_fp8_sdwa v[226:227], v13 src0_sel:WORD_1
	v_and_b32_e32 v172, 0xffff0000, v155
	v_pk_fma_f32 v[206:207], v[172:173], v[220:221], v[206:207] op_sel_hi:[0,1,1]
	v_cvt_pk_f32_fp8_e32 v[220:221], v14
	v_pk_fma_f32 v[208:209], v[172:173], v[222:223], v[208:209] op_sel_hi:[0,1,1]
	v_pk_fma_f32 v[210:211], v[172:173], v[224:225], v[210:211] op_sel_hi:[0,1,1]
	v_pk_fma_f32 v[212:213], v[172:173], v[226:227], v[212:213] op_sel_hi:[0,1,1]
	v_cvt_pk_f32_fp8_sdwa v[222:223], v14 src0_sel:WORD_1
	v_cvt_pk_f32_fp8_e32 v[224:225], v15
	v_cvt_pk_f32_fp8_sdwa v[226:227], v15 src0_sel:WORD_1
	v_pk_fma_f32 v[214:215], v[172:173], v[220:221], v[214:215] op_sel_hi:[0,1,1]
	s_waitcnt vmcnt(11)
	v_cvt_pk_f32_fp8_e32 v[220:221], v16
	v_pk_fma_f32 v[216:217], v[172:173], v[222:223], v[216:217] op_sel_hi:[0,1,1]
	v_pk_fma_f32 v[218:219], v[172:173], v[224:225], v[218:219] op_sel_hi:[0,1,1]
	v_pk_fma_f32 v[142:143], v[172:173], v[226:227], v[142:143] op_sel_hi:[0,1,1]
	v_cvt_pk_f32_fp8_sdwa v[222:223], v16 src0_sel:WORD_1
	v_cvt_pk_f32_fp8_e32 v[224:225], v17
	v_cvt_pk_f32_fp8_sdwa v[226:227], v17 src0_sel:WORD_1
	v_and_b32_e32 v172, 0xffff0000, v157
	v_pk_fma_f32 v[206:207], v[172:173], v[220:221], v[206:207] op_sel_hi:[0,1,1]
	v_cvt_pk_f32_fp8_e32 v[220:221], v18
	v_pk_fma_f32 v[208:209], v[172:173], v[222:223], v[208:209] op_sel_hi:[0,1,1]
	v_pk_fma_f32 v[210:211], v[172:173], v[224:225], v[210:211] op_sel_hi:[0,1,1]
	v_pk_fma_f32 v[212:213], v[172:173], v[226:227], v[212:213] op_sel_hi:[0,1,1]
	v_cvt_pk_f32_fp8_sdwa v[222:223], v18 src0_sel:WORD_1
	v_cvt_pk_f32_fp8_e32 v[224:225], v19
	v_cvt_pk_f32_fp8_sdwa v[226:227], v19 src0_sel:WORD_1
	v_pk_fma_f32 v[214:215], v[172:173], v[220:221], v[214:215] op_sel_hi:[0,1,1]
	s_waitcnt vmcnt(10)
	v_cvt_pk_f32_fp8_e32 v[220:221], v20
	v_pk_fma_f32 v[216:217], v[172:173], v[222:223], v[216:217] op_sel_hi:[0,1,1]
	v_pk_fma_f32 v[218:219], v[172:173], v[224:225], v[218:219] op_sel_hi:[0,1,1]
	v_pk_fma_f32 v[142:143], v[172:173], v[226:227], v[142:143] op_sel_hi:[0,1,1]
	v_cvt_pk_f32_fp8_sdwa v[222:223], v20 src0_sel:WORD_1
	v_cvt_pk_f32_fp8_e32 v[224:225], v21
	v_cvt_pk_f32_fp8_sdwa v[226:227], v21 src0_sel:WORD_1
	v_and_b32_e32 v172, 0xffff0000, v159
	v_pk_fma_f32 v[206:207], v[172:173], v[220:221], v[206:207] op_sel_hi:[0,1,1]
	v_cvt_pk_f32_fp8_e32 v[220:221], v22
	v_pk_fma_f32 v[208:209], v[172:173], v[222:223], v[208:209] op_sel_hi:[0,1,1]
	v_pk_fma_f32 v[210:211], v[172:173], v[224:225], v[210:211] op_sel_hi:[0,1,1]
	v_pk_fma_f32 v[212:213], v[172:173], v[226:227], v[212:213] op_sel_hi:[0,1,1]
	v_cvt_pk_f32_fp8_sdwa v[222:223], v22 src0_sel:WORD_1
	v_cvt_pk_f32_fp8_e32 v[224:225], v23
	v_cvt_pk_f32_fp8_sdwa v[226:227], v23 src0_sel:WORD_1
	v_pk_fma_f32 v[214:215], v[172:173], v[220:221], v[214:215] op_sel_hi:[0,1,1]
	s_waitcnt vmcnt(9)
	v_cvt_pk_f32_fp8_e32 v[220:221], v24
	v_pk_fma_f32 v[216:217], v[172:173], v[222:223], v[216:217] op_sel_hi:[0,1,1]
	v_pk_fma_f32 v[218:219], v[172:173], v[224:225], v[218:219] op_sel_hi:[0,1,1]
	v_pk_fma_f32 v[142:143], v[172:173], v[226:227], v[142:143] op_sel_hi:[0,1,1]
	v_cvt_pk_f32_fp8_sdwa v[222:223], v24 src0_sel:WORD_1
	v_cvt_pk_f32_fp8_e32 v[224:225], v25
	v_cvt_pk_f32_fp8_sdwa v[226:227], v25 src0_sel:WORD_1
	v_and_b32_e32 v172, 0xffff0000, v160
	v_pk_fma_f32 v[206:207], v[172:173], v[220:221], v[206:207] op_sel_hi:[0,1,1]
	v_cvt_pk_f32_fp8_e32 v[220:221], v26
	v_pk_fma_f32 v[208:209], v[172:173], v[222:223], v[208:209] op_sel_hi:[0,1,1]
	v_pk_fma_f32 v[210:211], v[172:173], v[224:225], v[210:211] op_sel_hi:[0,1,1]
	v_pk_fma_f32 v[212:213], v[172:173], v[226:227], v[212:213] op_sel_hi:[0,1,1]
	v_cvt_pk_f32_fp8_sdwa v[222:223], v26 src0_sel:WORD_1
	v_cvt_pk_f32_fp8_e32 v[224:225], v27
	v_cvt_pk_f32_fp8_sdwa v[226:227], v27 src0_sel:WORD_1
	v_pk_fma_f32 v[214:215], v[172:173], v[220:221], v[214:215] op_sel_hi:[0,1,1]
	s_waitcnt vmcnt(8)
	v_cvt_pk_f32_fp8_e32 v[220:221], v28
	v_pk_fma_f32 v[216:217], v[172:173], v[222:223], v[216:217] op_sel_hi:[0,1,1]
	v_pk_fma_f32 v[218:219], v[172:173], v[224:225], v[218:219] op_sel_hi:[0,1,1]
	v_pk_fma_f32 v[142:143], v[172:173], v[226:227], v[142:143] op_sel_hi:[0,1,1]
	v_cvt_pk_f32_fp8_sdwa v[222:223], v28 src0_sel:WORD_1
	v_cvt_pk_f32_fp8_e32 v[224:225], v29
	v_cvt_pk_f32_fp8_sdwa v[226:227], v29 src0_sel:WORD_1
	v_and_b32_e32 v172, 0xffff0000, v161
	v_pk_fma_f32 v[206:207], v[172:173], v[220:221], v[206:207] op_sel_hi:[0,1,1]
	v_cvt_pk_f32_fp8_e32 v[220:221], v30
	v_pk_fma_f32 v[208:209], v[172:173], v[222:223], v[208:209] op_sel_hi:[0,1,1]
	v_pk_fma_f32 v[210:211], v[172:173], v[224:225], v[210:211] op_sel_hi:[0,1,1]
	v_pk_fma_f32 v[212:213], v[172:173], v[226:227], v[212:213] op_sel_hi:[0,1,1]
	v_cvt_pk_f32_fp8_sdwa v[222:223], v30 src0_sel:WORD_1
	v_cvt_pk_f32_fp8_e32 v[224:225], v31
	v_cvt_pk_f32_fp8_sdwa v[226:227], v31 src0_sel:WORD_1
	v_pk_fma_f32 v[214:215], v[172:173], v[220:221], v[214:215] op_sel_hi:[0,1,1]
	s_waitcnt vmcnt(7)
	v_cvt_pk_f32_fp8_e32 v[220:221], v32
	v_pk_fma_f32 v[216:217], v[172:173], v[222:223], v[216:217] op_sel_hi:[0,1,1]
	v_pk_fma_f32 v[218:219], v[172:173], v[224:225], v[218:219] op_sel_hi:[0,1,1]
	v_pk_fma_f32 v[142:143], v[172:173], v[226:227], v[142:143] op_sel_hi:[0,1,1]
	v_cvt_pk_f32_fp8_sdwa v[222:223], v32 src0_sel:WORD_1
	v_cvt_pk_f32_fp8_e32 v[224:225], v33
	v_cvt_pk_f32_fp8_sdwa v[226:227], v33 src0_sel:WORD_1
	v_and_b32_e32 v172, 0xffff0000, v162
	v_pk_fma_f32 v[206:207], v[172:173], v[220:221], v[206:207] op_sel_hi:[0,1,1]
	v_cvt_pk_f32_fp8_e32 v[220:221], v34
	v_pk_fma_f32 v[208:209], v[172:173], v[222:223], v[208:209] op_sel_hi:[0,1,1]
	v_pk_fma_f32 v[210:211], v[172:173], v[224:225], v[210:211] op_sel_hi:[0,1,1]
	v_pk_fma_f32 v[212:213], v[172:173], v[226:227], v[212:213] op_sel_hi:[0,1,1]
	v_cvt_pk_f32_fp8_sdwa v[222:223], v34 src0_sel:WORD_1
	v_cvt_pk_f32_fp8_e32 v[224:225], v35
	v_cvt_pk_f32_fp8_sdwa v[226:227], v35 src0_sel:WORD_1
	v_pk_fma_f32 v[214:215], v[172:173], v[220:221], v[214:215] op_sel_hi:[0,1,1]
	s_waitcnt vmcnt(6)
	v_cvt_pk_f32_fp8_e32 v[220:221], v36
	v_pk_fma_f32 v[216:217], v[172:173], v[222:223], v[216:217] op_sel_hi:[0,1,1]
	v_pk_fma_f32 v[218:219], v[172:173], v[224:225], v[218:219] op_sel_hi:[0,1,1]
	v_pk_fma_f32 v[142:143], v[172:173], v[226:227], v[142:143] op_sel_hi:[0,1,1]
	v_cvt_pk_f32_fp8_sdwa v[222:223], v36 src0_sel:WORD_1
	v_cvt_pk_f32_fp8_e32 v[224:225], v37
	v_cvt_pk_f32_fp8_sdwa v[226:227], v37 src0_sel:WORD_1
	v_and_b32_e32 v172, 0xffff0000, v163
	v_pk_fma_f32 v[206:207], v[172:173], v[220:221], v[206:207] op_sel_hi:[0,1,1]
	v_cvt_pk_f32_fp8_e32 v[220:221], v38
	v_pk_fma_f32 v[208:209], v[172:173], v[222:223], v[208:209] op_sel_hi:[0,1,1]
	v_pk_fma_f32 v[210:211], v[172:173], v[224:225], v[210:211] op_sel_hi:[0,1,1]
	v_pk_fma_f32 v[212:213], v[172:173], v[226:227], v[212:213] op_sel_hi:[0,1,1]
	v_cvt_pk_f32_fp8_sdwa v[222:223], v38 src0_sel:WORD_1
	v_cvt_pk_f32_fp8_e32 v[224:225], v39
	v_cvt_pk_f32_fp8_sdwa v[226:227], v39 src0_sel:WORD_1
	v_pk_fma_f32 v[214:215], v[172:173], v[220:221], v[214:215] op_sel_hi:[0,1,1]
	s_waitcnt vmcnt(5)
	v_cvt_pk_f32_fp8_e32 v[220:221], v40
	v_pk_fma_f32 v[216:217], v[172:173], v[222:223], v[216:217] op_sel_hi:[0,1,1]
	v_pk_fma_f32 v[218:219], v[172:173], v[224:225], v[218:219] op_sel_hi:[0,1,1]
	v_pk_fma_f32 v[142:143], v[172:173], v[226:227], v[142:143] op_sel_hi:[0,1,1]
	v_cvt_pk_f32_fp8_sdwa v[222:223], v40 src0_sel:WORD_1
	v_cvt_pk_f32_fp8_e32 v[224:225], v41
	v_cvt_pk_f32_fp8_sdwa v[226:227], v41 src0_sel:WORD_1
	v_and_b32_e32 v172, 0xffff0000, v164
	v_pk_fma_f32 v[206:207], v[172:173], v[220:221], v[206:207] op_sel_hi:[0,1,1]
	v_cvt_pk_f32_fp8_e32 v[220:221], v42
	v_pk_fma_f32 v[208:209], v[172:173], v[222:223], v[208:209] op_sel_hi:[0,1,1]
	v_pk_fma_f32 v[210:211], v[172:173], v[224:225], v[210:211] op_sel_hi:[0,1,1]
	v_pk_fma_f32 v[212:213], v[172:173], v[226:227], v[212:213] op_sel_hi:[0,1,1]
	v_cvt_pk_f32_fp8_sdwa v[222:223], v42 src0_sel:WORD_1
	v_cvt_pk_f32_fp8_e32 v[224:225], v43
	v_cvt_pk_f32_fp8_sdwa v[226:227], v43 src0_sel:WORD_1
	v_pk_fma_f32 v[214:215], v[172:173], v[220:221], v[214:215] op_sel_hi:[0,1,1]
	s_waitcnt vmcnt(4)
	v_cvt_pk_f32_fp8_e32 v[220:221], v44
	v_pk_fma_f32 v[216:217], v[172:173], v[222:223], v[216:217] op_sel_hi:[0,1,1]
	v_pk_fma_f32 v[218:219], v[172:173], v[224:225], v[218:219] op_sel_hi:[0,1,1]
	v_pk_fma_f32 v[142:143], v[172:173], v[226:227], v[142:143] op_sel_hi:[0,1,1]
	v_cvt_pk_f32_fp8_sdwa v[222:223], v44 src0_sel:WORD_1
	v_cvt_pk_f32_fp8_e32 v[224:225], v45
	v_cvt_pk_f32_fp8_sdwa v[226:227], v45 src0_sel:WORD_1
	v_and_b32_e32 v172, 0xffff0000, v165
	v_pk_fma_f32 v[206:207], v[172:173], v[220:221], v[206:207] op_sel_hi:[0,1,1]
	v_cvt_pk_f32_fp8_e32 v[220:221], v46
	v_pk_fma_f32 v[208:209], v[172:173], v[222:223], v[208:209] op_sel_hi:[0,1,1]
	v_pk_fma_f32 v[210:211], v[172:173], v[224:225], v[210:211] op_sel_hi:[0,1,1]
	v_pk_fma_f32 v[212:213], v[172:173], v[226:227], v[212:213] op_sel_hi:[0,1,1]
	v_cvt_pk_f32_fp8_sdwa v[222:223], v46 src0_sel:WORD_1
	v_cvt_pk_f32_fp8_e32 v[224:225], v47
	v_cvt_pk_f32_fp8_sdwa v[226:227], v47 src0_sel:WORD_1
	v_pk_fma_f32 v[214:215], v[172:173], v[220:221], v[214:215] op_sel_hi:[0,1,1]
	s_waitcnt vmcnt(3)
	v_cvt_pk_f32_fp8_e32 v[220:221], v48
	v_pk_fma_f32 v[216:217], v[172:173], v[222:223], v[216:217] op_sel_hi:[0,1,1]
	v_pk_fma_f32 v[218:219], v[172:173], v[224:225], v[218:219] op_sel_hi:[0,1,1]
	v_pk_fma_f32 v[142:143], v[172:173], v[226:227], v[142:143] op_sel_hi:[0,1,1]
	v_cvt_pk_f32_fp8_sdwa v[222:223], v48 src0_sel:WORD_1
	v_cvt_pk_f32_fp8_e32 v[224:225], v49
	v_cvt_pk_f32_fp8_sdwa v[226:227], v49 src0_sel:WORD_1
	v_and_b32_e32 v172, 0xffff0000, v185
	v_pk_fma_f32 v[206:207], v[172:173], v[220:221], v[206:207] op_sel_hi:[0,1,1]
	v_cvt_pk_f32_fp8_e32 v[220:221], v50
	v_pk_fma_f32 v[208:209], v[172:173], v[222:223], v[208:209] op_sel_hi:[0,1,1]
	v_pk_fma_f32 v[210:211], v[172:173], v[224:225], v[210:211] op_sel_hi:[0,1,1]
	v_pk_fma_f32 v[212:213], v[172:173], v[226:227], v[212:213] op_sel_hi:[0,1,1]
	v_cvt_pk_f32_fp8_sdwa v[222:223], v50 src0_sel:WORD_1
	v_cvt_pk_f32_fp8_e32 v[224:225], v51
	v_cvt_pk_f32_fp8_sdwa v[226:227], v51 src0_sel:WORD_1
	v_pk_fma_f32 v[214:215], v[172:173], v[220:221], v[214:215] op_sel_hi:[0,1,1]
	s_waitcnt vmcnt(2)
	v_cvt_pk_f32_fp8_e32 v[220:221], v52
	v_pk_fma_f32 v[216:217], v[172:173], v[222:223], v[216:217] op_sel_hi:[0,1,1]
	v_pk_fma_f32 v[218:219], v[172:173], v[224:225], v[218:219] op_sel_hi:[0,1,1]
	v_pk_fma_f32 v[142:143], v[172:173], v[226:227], v[142:143] op_sel_hi:[0,1,1]
	v_cvt_pk_f32_fp8_sdwa v[222:223], v52 src0_sel:WORD_1
	v_cvt_pk_f32_fp8_e32 v[224:225], v53
	v_cvt_pk_f32_fp8_sdwa v[226:227], v53 src0_sel:WORD_1
	v_and_b32_e32 v172, 0xffff0000, v186
	v_pk_fma_f32 v[206:207], v[172:173], v[220:221], v[206:207] op_sel_hi:[0,1,1]
	v_cvt_pk_f32_fp8_e32 v[220:221], v54
	v_pk_fma_f32 v[208:209], v[172:173], v[222:223], v[208:209] op_sel_hi:[0,1,1]
	v_pk_fma_f32 v[210:211], v[172:173], v[224:225], v[210:211] op_sel_hi:[0,1,1]
	v_pk_fma_f32 v[212:213], v[172:173], v[226:227], v[212:213] op_sel_hi:[0,1,1]
	v_cvt_pk_f32_fp8_sdwa v[222:223], v54 src0_sel:WORD_1
	v_cvt_pk_f32_fp8_e32 v[224:225], v55
	v_cvt_pk_f32_fp8_sdwa v[226:227], v55 src0_sel:WORD_1
	v_pk_fma_f32 v[214:215], v[172:173], v[220:221], v[214:215] op_sel_hi:[0,1,1]
	s_waitcnt vmcnt(1)
	v_cvt_pk_f32_fp8_e32 v[220:221], v56
	v_pk_fma_f32 v[216:217], v[172:173], v[222:223], v[216:217] op_sel_hi:[0,1,1]
	v_pk_fma_f32 v[218:219], v[172:173], v[224:225], v[218:219] op_sel_hi:[0,1,1]
	v_pk_fma_f32 v[142:143], v[172:173], v[226:227], v[142:143] op_sel_hi:[0,1,1]
	v_cvt_pk_f32_fp8_sdwa v[222:223], v56 src0_sel:WORD_1
	v_cvt_pk_f32_fp8_e32 v[224:225], v57
	v_cvt_pk_f32_fp8_sdwa v[226:227], v57 src0_sel:WORD_1
	v_and_b32_e32 v172, 0xffff0000, v187
	v_pk_fma_f32 v[206:207], v[172:173], v[220:221], v[206:207] op_sel_hi:[0,1,1]
	v_cvt_pk_f32_fp8_e32 v[220:221], v58
	v_pk_fma_f32 v[208:209], v[172:173], v[222:223], v[208:209] op_sel_hi:[0,1,1]
	v_pk_fma_f32 v[210:211], v[172:173], v[224:225], v[210:211] op_sel_hi:[0,1,1]
	v_pk_fma_f32 v[212:213], v[172:173], v[226:227], v[212:213] op_sel_hi:[0,1,1]
	v_cvt_pk_f32_fp8_sdwa v[222:223], v58 src0_sel:WORD_1
	v_cvt_pk_f32_fp8_e32 v[224:225], v59
	v_cvt_pk_f32_fp8_sdwa v[226:227], v59 src0_sel:WORD_1
	v_pk_fma_f32 v[214:215], v[172:173], v[220:221], v[214:215] op_sel_hi:[0,1,1]
	s_waitcnt vmcnt(0)
	v_cvt_pk_f32_fp8_e32 v[220:221], v68
	v_pk_fma_f32 v[216:217], v[172:173], v[222:223], v[216:217] op_sel_hi:[0,1,1]
	v_pk_fma_f32 v[218:219], v[172:173], v[224:225], v[218:219] op_sel_hi:[0,1,1]
	v_pk_fma_f32 v[142:143], v[172:173], v[226:227], v[142:143] op_sel_hi:[0,1,1]
	v_cvt_pk_f32_fp8_sdwa v[222:223], v68 src0_sel:WORD_1
	v_cvt_pk_f32_fp8_e32 v[224:225], v69
	v_cvt_pk_f32_fp8_sdwa v[226:227], v69 src0_sel:WORD_1
	v_and_b32_e32 v172, 0xffff0000, v188
	v_pk_fma_f32 v[206:207], v[172:173], v[220:221], v[206:207] op_sel_hi:[0,1,1]
	v_cvt_pk_f32_fp8_e32 v[220:221], v70
	v_pk_fma_f32 v[208:209], v[172:173], v[222:223], v[208:209] op_sel_hi:[0,1,1]
	v_pk_fma_f32 v[210:211], v[172:173], v[224:225], v[210:211] op_sel_hi:[0,1,1]
	v_pk_fma_f32 v[212:213], v[172:173], v[226:227], v[212:213] op_sel_hi:[0,1,1]
	v_cvt_pk_f32_fp8_sdwa v[222:223], v70 src0_sel:WORD_1
	v_cvt_pk_f32_fp8_e32 v[224:225], v71
	v_cvt_pk_f32_fp8_sdwa v[226:227], v71 src0_sel:WORD_1
	v_pk_fma_f32 v[214:215], v[172:173], v[220:221], v[214:215] op_sel_hi:[0,1,1]
	v_pk_fma_f32 v[216:217], v[172:173], v[222:223], v[216:217] op_sel_hi:[0,1,1]
	v_pk_fma_f32 v[218:219], v[172:173], v[224:225], v[218:219] op_sel_hi:[0,1,1]
	v_pk_fma_f32 v[142:143], v[172:173], v[226:227], v[142:143] op_sel_hi:[0,1,1]
	v_permlane32_swap_b32_e32 v206, v214
	v_permlane32_swap_b32_e32 v207, v215
	v_permlane32_swap_b32_e32 v210, v218
	v_permlane32_swap_b32_e32 v211, v219
	v_permlane32_swap_b32_e32 v208, v216
	v_permlane32_swap_b32_e32 v209, v217
	v_permlane32_swap_b32_e32 v212, v142
	v_permlane32_swap_b32_e32 v213, v143
	v_pk_add_f32 v[206:207], v[206:207], v[214:215]
	v_pk_add_f32 v[210:211], v[210:211], v[218:219]
	v_pk_add_f32 v[208:209], v[208:209], v[216:217]
	v_pk_add_f32 v[142:143], v[212:213], v[142:143]
	s_nop 1
	v_permlane16_swap_b32_e32 v206, v210
	v_permlane16_swap_b32_e32 v207, v211
	v_permlane16_swap_b32_e32 v208, v142
	v_permlane16_swap_b32_e32 v209, v143
	v_pk_add_f32 v[206:207], v[206:207], v[210:211]
	v_pk_add_f32 v[142:143], v[208:209], v[142:143]
	s_nop 1
	v_add_f32_dpp v142, v142, v142 row_ror:8 row_mask:0xf bank_mask:0xc
	v_add_f32_dpp v142, v206, v206 row_ror:8 row_mask:0xf bank_mask:0x3
	v_add_f32_dpp v143, v143, v143 row_ror:8 row_mask:0xf bank_mask:0xc
	v_add_f32_dpp v143, v207, v207 row_ror:8 row_mask:0xf bank_mask:0x3
	s_waitcnt lgkmcnt(0)
	v_ashrrev_i32_e32 v175, 31, v174
	v_lshlrev_b64 v[206:207], 12, v[174:175]
	v_lshl_add_u64 v[206:207], v[132:133], 0, v[206:207]
	s_nop 0
	v_pk_add_f32 v[140:141], v[142:143], v[140:141]
	global_store_dwordx2 v[206:207], v[140:141], off
	v_pk_mul_f32 v[140:141], v[140:141], v[140:141]
	s_nop 0
	v_add_f32_e32 v137, v140, v141
	v_mov_b32_e32 v140, 0
	s_nop 0
	v_add_f32_dpp v137, v137, v137 quad_perm:[1,0,3,2] row_mask:0xf bank_mask:0xf bound_ctrl:1
	s_nop 1
	v_add_f32_dpp v137, v137, v137 quad_perm:[2,3,0,1] row_mask:0xf bank_mask:0xf bound_ctrl:1
	s_nop 1
	v_add_f32_dpp v137, v137, v137 row_half_mirror row_mask:0xf bank_mask:0xf bound_ctrl:1
	s_nop 1
	v_add_f32_dpp v137, v137, v137 row_mirror row_mask:0xf bank_mask:0xf bound_ctrl:1
	s_nop 1
	v_mov_b32_dpp v140, v137 row_bcast:15 row_mask:0xa bank_mask:0xf
	v_add_f32_e32 v137, v137, v140
	v_mov_b32_e32 v140, 0
	s_nop 1
	v_mov_b32_dpp v140, v137 row_bcast:31 row_mask:0xc bank_mask:0xf
	v_add_f32_e32 v137, v137, v140
	s_nop 0
	v_readlane_b32 s16, v137, 63
	s_and_saveexec_b64 s[14:15], s[6:7]
	s_cbranch_execz .LBB0_1153
	v_lshl_add_u64 v[140:141], v[174:175], 2, s[30:31]
	v_mov_b32_e32 v137, s16
	global_store_dword v[140:141], v137, off

.LBB0_1158:
	s_or_b64 exec, exec, s[12:13]
	v_cvt_pk_f32_fp8_e32 v[174:175], v64
	v_cvt_pk_f32_fp8_sdwa v[206:207], v64 src0_sel:WORD_1
	v_cvt_pk_f32_fp8_e32 v[208:209], v65
	v_cvt_pk_f32_fp8_sdwa v[210:211], v65 src0_sel:WORD_1
	v_cvt_pk_f32_fp8_e32 v[212:213], v66
	v_cvt_pk_f32_fp8_sdwa v[214:215], v66 src0_sel:WORD_1
	v_cvt_pk_f32_fp8_e32 v[216:217], v67
	v_cvt_pk_f32_fp8_sdwa v[218:219], v67 src0_sel:WORD_1
	v_and_b32_e32 v140, 0xffff0000, v189
	v_pk_fma_f32 v[174:175], v[140:141], v[174:175], 0 op_sel_hi:[0,1,0]
	v_pk_fma_f32 v[206:207], v[140:141], v[206:207], 0 op_sel_hi:[0,1,0]
	v_pk_fma_f32 v[208:209], v[140:141], v[208:209], 0 op_sel_hi:[0,1,0]
	v_pk_fma_f32 v[210:211], v[140:141], v[210:211], 0 op_sel_hi:[0,1,0]
	v_pk_fma_f32 v[212:213], v[140:141], v[212:213], 0 op_sel_hi:[0,1,0]
	v_pk_fma_f32 v[214:215], v[140:141], v[214:215], 0 op_sel_hi:[0,1,0]
	v_pk_fma_f32 v[216:217], v[140:141], v[216:217], 0 op_sel_hi:[0,1,0]
	v_pk_fma_f32 v[140:141], v[140:141], v[218:219], 0 op_sel_hi:[0,1,0]
	v_cvt_pk_f32_fp8_e32 v[218:219], v60
	v_cvt_pk_f32_fp8_sdwa v[220:221], v60 src0_sel:WORD_1
	v_cvt_pk_f32_fp8_e32 v[222:223], v61
	v_cvt_pk_f32_fp8_sdwa v[224:225], v61 src0_sel:WORD_1
	v_and_b32_e32 v172, 0xffff0000, v190
	v_pk_fma_f32 v[174:175], v[172:173], v[218:219], v[174:175] op_sel_hi:[0,1,1]
	v_cvt_pk_f32_fp8_e32 v[218:219], v62
	v_pk_fma_f32 v[206:207], v[172:173], v[220:221], v[206:207] op_sel_hi:[0,1,1]
	v_pk_fma_f32 v[208:209], v[172:173], v[222:223], v[208:209] op_sel_hi:[0,1,1]
	v_pk_fma_f32 v[210:211], v[172:173], v[224:225], v[210:211] op_sel_hi:[0,1,1]
	v_cvt_pk_f32_fp8_sdwa v[220:221], v62 src0_sel:WORD_1
	v_cvt_pk_f32_fp8_e32 v[222:223], v63
	v_cvt_pk_f32_fp8_sdwa v[224:225], v63 src0_sel:WORD_1
	v_pk_fma_f32 v[212:213], v[172:173], v[218:219], v[212:213] op_sel_hi:[0,1,1]
	v_cvt_pk_f32_fp8_e32 v[218:219], v76
	v_pk_fma_f32 v[214:215], v[172:173], v[220:221], v[214:215] op_sel_hi:[0,1,1]
	v_pk_fma_f32 v[216:217], v[172:173], v[222:223], v[216:217] op_sel_hi:[0,1,1]
	v_pk_fma_f32 v[140:141], v[172:173], v[224:225], v[140:141] op_sel_hi:[0,1,1]
	v_cvt_pk_f32_fp8_sdwa v[220:221], v76 src0_sel:WORD_1
	v_cvt_pk_f32_fp8_e32 v[222:223], v77
	v_cvt_pk_f32_fp8_sdwa v[224:225], v77 src0_sel:WORD_1
	v_and_b32_e32 v172, 0xffff0000, v191
	v_pk_fma_f32 v[174:175], v[172:173], v[218:219], v[174:175] op_sel_hi:[0,1,1]
	v_cvt_pk_f32_fp8_e32 v[218:219], v78
	v_pk_fma_f32 v[206:207], v[172:173], v[220:221], v[206:207] op_sel_hi:[0,1,1]
	v_pk_fma_f32 v[208:209], v[172:173], v[222:223], v[208:209] op_sel_hi:[0,1,1]
	v_pk_fma_f32 v[210:211], v[172:173], v[224:225], v[210:211] op_sel_hi:[0,1,1]
	v_cvt_pk_f32_fp8_sdwa v[220:221], v78 src0_sel:WORD_1
	v_cvt_pk_f32_fp8_e32 v[222:223], v79
	v_cvt_pk_f32_fp8_sdwa v[224:225], v79 src0_sel:WORD_1
	v_pk_fma_f32 v[212:213], v[172:173], v[218:219], v[212:213] op_sel_hi:[0,1,1]
	v_cvt_pk_f32_fp8_e32 v[218:219], v72
	v_pk_fma_f32 v[214:215], v[172:173], v[220:221], v[214:215] op_sel_hi:[0,1,1]
	v_pk_fma_f32 v[216:217], v[172:173], v[222:223], v[216:217] op_sel_hi:[0,1,1]
	v_pk_fma_f32 v[140:141], v[172:173], v[224:225], v[140:141] op_sel_hi:[0,1,1]
	v_cvt_pk_f32_fp8_sdwa v[220:221], v72 src0_sel:WORD_1
	v_cvt_pk_f32_fp8_e32 v[222:223], v73
	v_cvt_pk_f32_fp8_sdwa v[224:225], v73 src0_sel:WORD_1
	v_and_b32_e32 v172, 0xffff0000, v192
	v_pk_fma_f32 v[174:175], v[172:173], v[218:219], v[174:175] op_sel_hi:[0,1,1]
	v_cvt_pk_f32_fp8_e32 v[218:219], v74
	v_pk_fma_f32 v[206:207], v[172:173], v[220:221], v[206:207] op_sel_hi:[0,1,1]
	v_pk_fma_f32 v[208:209], v[172:173], v[222:223], v[208:209] op_sel_hi:[0,1,1]
	v_pk_fma_f32 v[210:211], v[172:173], v[224:225], v[210:211] op_sel_hi:[0,1,1]
	v_cvt_pk_f32_fp8_sdwa v[220:221], v74 src0_sel:WORD_1
	v_cvt_pk_f32_fp8_e32 v[222:223], v75
	v_cvt_pk_f32_fp8_sdwa v[224:225], v75 src0_sel:WORD_1
	v_pk_fma_f32 v[212:213], v[172:173], v[218:219], v[212:213] op_sel_hi:[0,1,1]
	v_cvt_pk_f32_fp8_e32 v[218:219], v84
	v_pk_fma_f32 v[214:215], v[172:173], v[220:221], v[214:215] op_sel_hi:[0,1,1]
	v_pk_fma_f32 v[216:217], v[172:173], v[222:223], v[216:217] op_sel_hi:[0,1,1]
	v_pk_fma_f32 v[140:141], v[172:173], v[224:225], v[140:141] op_sel_hi:[0,1,1]
	v_cvt_pk_f32_fp8_sdwa v[220:221], v84 src0_sel:WORD_1
	v_cvt_pk_f32_fp8_e32 v[222:223], v85
	v_cvt_pk_f32_fp8_sdwa v[224:225], v85 src0_sel:WORD_1
	v_and_b32_e32 v172, 0xffff0000, v193
	v_pk_fma_f32 v[174:175], v[172:173], v[218:219], v[174:175] op_sel_hi:[0,1,1]
	v_cvt_pk_f32_fp8_e32 v[218:219], v86
	v_pk_fma_f32 v[206:207], v[172:173], v[220:221], v[206:207] op_sel_hi:[0,1,1]
	v_pk_fma_f32 v[208:209], v[172:173], v[222:223], v[208:209] op_sel_hi:[0,1,1]
	v_pk_fma_f32 v[210:211], v[172:173], v[224:225], v[210:211] op_sel_hi:[0,1,1]
	v_cvt_pk_f32_fp8_sdwa v[220:221], v86 src0_sel:WORD_1
	v_cvt_pk_f32_fp8_e32 v[222:223], v87
	v_cvt_pk_f32_fp8_sdwa v[224:225], v87 src0_sel:WORD_1
	v_pk_fma_f32 v[212:213], v[172:173], v[218:219], v[212:213] op_sel_hi:[0,1,1]
	v_cvt_pk_f32_fp8_e32 v[218:219], v80
	v_pk_fma_f32 v[214:215], v[172:173], v[220:221], v[214:215] op_sel_hi:[0,1,1]
	v_pk_fma_f32 v[216:217], v[172:173], v[222:223], v[216:217] op_sel_hi:[0,1,1]
	v_pk_fma_f32 v[140:141], v[172:173], v[224:225], v[140:141] op_sel_hi:[0,1,1]
	v_cvt_pk_f32_fp8_sdwa v[220:221], v80 src0_sel:WORD_1
	v_cvt_pk_f32_fp8_e32 v[222:223], v81
	v_cvt_pk_f32_fp8_sdwa v[224:225], v81 src0_sel:WORD_1
	v_and_b32_e32 v172, 0xffff0000, v194
	v_pk_fma_f32 v[174:175], v[172:173], v[218:219], v[174:175] op_sel_hi:[0,1,1]
	v_cvt_pk_f32_fp8_e32 v[218:219], v82
	v_pk_fma_f32 v[206:207], v[172:173], v[220:221], v[206:207] op_sel_hi:[0,1,1]
	v_pk_fma_f32 v[208:209], v[172:173], v[222:223], v[208:209] op_sel_hi:[0,1,1]
	v_pk_fma_f32 v[210:211], v[172:173], v[224:225], v[210:211] op_sel_hi:[0,1,1]
	v_cvt_pk_f32_fp8_sdwa v[220:221], v82 src0_sel:WORD_1
	v_cvt_pk_f32_fp8_e32 v[222:223], v83
	v_cvt_pk_f32_fp8_sdwa v[224:225], v83 src0_sel:WORD_1
	v_pk_fma_f32 v[212:213], v[172:173], v[218:219], v[212:213] op_sel_hi:[0,1,1]
	v_cvt_pk_f32_fp8_e32 v[218:219], v92
	v_pk_fma_f32 v[214:215], v[172:173], v[220:221], v[214:215] op_sel_hi:[0,1,1]
	v_pk_fma_f32 v[216:217], v[172:173], v[222:223], v[216:217] op_sel_hi:[0,1,1]
	v_pk_fma_f32 v[140:141], v[172:173], v[224:225], v[140:141] op_sel_hi:[0,1,1]
	v_cvt_pk_f32_fp8_sdwa v[220:221], v92 src0_sel:WORD_1
	v_cvt_pk_f32_fp8_e32 v[222:223], v93
	v_cvt_pk_f32_fp8_sdwa v[224:225], v93 src0_sel:WORD_1
	v_and_b32_e32 v172, 0xffff0000, v195
	v_pk_fma_f32 v[174:175], v[172:173], v[218:219], v[174:175] op_sel_hi:[0,1,1]
	v_cvt_pk_f32_fp8_e32 v[218:219], v94
	v_pk_fma_f32 v[206:207], v[172:173], v[220:221], v[206:207] op_sel_hi:[0,1,1]
	v_pk_fma_f32 v[208:209], v[172:173], v[222:223], v[208:209] op_sel_hi:[0,1,1]
	v_pk_fma_f32 v[210:211], v[172:173], v[224:225], v[210:211] op_sel_hi:[0,1,1]
	v_cvt_pk_f32_fp8_sdwa v[220:221], v94 src0_sel:WORD_1
	v_cvt_pk_f32_fp8_e32 v[222:223], v95
	v_cvt_pk_f32_fp8_sdwa v[224:225], v95 src0_sel:WORD_1
	v_pk_fma_f32 v[212:213], v[172:173], v[218:219], v[212:213] op_sel_hi:[0,1,1]
	v_cvt_pk_f32_fp8_e32 v[218:219], v88
	v_pk_fma_f32 v[214:215], v[172:173], v[220:221], v[214:215] op_sel_hi:[0,1,1]
	v_pk_fma_f32 v[216:217], v[172:173], v[222:223], v[216:217] op_sel_hi:[0,1,1]
	v_pk_fma_f32 v[140:141], v[172:173], v[224:225], v[140:141] op_sel_hi:[0,1,1]
	v_cvt_pk_f32_fp8_sdwa v[220:221], v88 src0_sel:WORD_1
	v_cvt_pk_f32_fp8_e32 v[222:223], v89
	v_cvt_pk_f32_fp8_sdwa v[224:225], v89 src0_sel:WORD_1
	v_and_b32_e32 v172, 0xffff0000, v196
	v_pk_fma_f32 v[174:175], v[172:173], v[218:219], v[174:175] op_sel_hi:[0,1,1]
	v_cvt_pk_f32_fp8_e32 v[218:219], v90
	v_pk_fma_f32 v[206:207], v[172:173], v[220:221], v[206:207] op_sel_hi:[0,1,1]
	v_pk_fma_f32 v[208:209], v[172:173], v[222:223], v[208:209] op_sel_hi:[0,1,1]
	v_pk_fma_f32 v[210:211], v[172:173], v[224:225], v[210:211] op_sel_hi:[0,1,1]
	v_cvt_pk_f32_fp8_sdwa v[220:221], v90 src0_sel:WORD_1
	v_cvt_pk_f32_fp8_e32 v[222:223], v91
	v_cvt_pk_f32_fp8_sdwa v[224:225], v91 src0_sel:WORD_1
	v_pk_fma_f32 v[212:213], v[172:173], v[218:219], v[212:213] op_sel_hi:[0,1,1]
	v_cvt_pk_f32_fp8_e32 v[218:219], v100
	v_pk_fma_f32 v[214:215], v[172:173], v[220:221], v[214:215] op_sel_hi:[0,1,1]
	v_pk_fma_f32 v[216:217], v[172:173], v[222:223], v[216:217] op_sel_hi:[0,1,1]
	v_pk_fma_f32 v[140:141], v[172:173], v[224:225], v[140:141] op_sel_hi:[0,1,1]
	v_cvt_pk_f32_fp8_sdwa v[220:221], v100 src0_sel:WORD_1
	v_cvt_pk_f32_fp8_e32 v[222:223], v101
	v_cvt_pk_f32_fp8_sdwa v[224:225], v101 src0_sel:WORD_1
	v_and_b32_e32 v172, 0xffff0000, v197
	v_pk_fma_f32 v[174:175], v[172:173], v[218:219], v[174:175] op_sel_hi:[0,1,1]
	v_cvt_pk_f32_fp8_e32 v[218:219], v102
	v_pk_fma_f32 v[206:207], v[172:173], v[220:221], v[206:207] op_sel_hi:[0,1,1]
	v_pk_fma_f32 v[208:209], v[172:173], v[222:223], v[208:209] op_sel_hi:[0,1,1]
	v_pk_fma_f32 v[210:211], v[172:173], v[224:225], v[210:211] op_sel_hi:[0,1,1]
	v_cvt_pk_f32_fp8_sdwa v[220:221], v102 src0_sel:WORD_1
	v_cvt_pk_f32_fp8_e32 v[222:223], v103
	v_cvt_pk_f32_fp8_sdwa v[224:225], v103 src0_sel:WORD_1
	v_pk_fma_f32 v[212:213], v[172:173], v[218:219], v[212:213] op_sel_hi:[0,1,1]
	v_cvt_pk_f32_fp8_e32 v[218:219], v96
	v_pk_fma_f32 v[214:215], v[172:173], v[220:221], v[214:215] op_sel_hi:[0,1,1]
	v_pk_fma_f32 v[216:217], v[172:173], v[222:223], v[216:217] op_sel_hi:[0,1,1]
	v_pk_fma_f32 v[140:141], v[172:173], v[224:225], v[140:141] op_sel_hi:[0,1,1]
	v_cvt_pk_f32_fp8_sdwa v[220:221], v96 src0_sel:WORD_1
	v_cvt_pk_f32_fp8_e32 v[222:223], v97
	v_cvt_pk_f32_fp8_sdwa v[224:225], v97 src0_sel:WORD_1
	v_and_b32_e32 v172, 0xffff0000, v198
	v_pk_fma_f32 v[174:175], v[172:173], v[218:219], v[174:175] op_sel_hi:[0,1,1]
	v_cvt_pk_f32_fp8_e32 v[218:219], v98
	v_pk_fma_f32 v[206:207], v[172:173], v[220:221], v[206:207] op_sel_hi:[0,1,1]
	v_pk_fma_f32 v[208:209], v[172:173], v[222:223], v[208:209] op_sel_hi:[0,1,1]
	v_pk_fma_f32 v[210:211], v[172:173], v[224:225], v[210:211] op_sel_hi:[0,1,1]
	v_cvt_pk_f32_fp8_sdwa v[220:221], v98 src0_sel:WORD_1
	v_cvt_pk_f32_fp8_e32 v[222:223], v99
	v_cvt_pk_f32_fp8_sdwa v[224:225], v99 src0_sel:WORD_1
	v_pk_fma_f32 v[212:213], v[172:173], v[218:219], v[212:213] op_sel_hi:[0,1,1]
	v_cvt_pk_f32_fp8_e32 v[218:219], v108
	v_pk_fma_f32 v[214:215], v[172:173], v[220:221], v[214:215] op_sel_hi:[0,1,1]
	v_pk_fma_f32 v[216:217], v[172:173], v[222:223], v[216:217] op_sel_hi:[0,1,1]
	v_pk_fma_f32 v[140:141], v[172:173], v[224:225], v[140:141] op_sel_hi:[0,1,1]
	v_cvt_pk_f32_fp8_sdwa v[220:221], v108 src0_sel:WORD_1
	v_cvt_pk_f32_fp8_e32 v[222:223], v109
	v_cvt_pk_f32_fp8_sdwa v[224:225], v109 src0_sel:WORD_1
	v_and_b32_e32 v172, 0xffff0000, v199
	v_pk_fma_f32 v[174:175], v[172:173], v[218:219], v[174:175] op_sel_hi:[0,1,1]
	v_cvt_pk_f32_fp8_e32 v[218:219], v110
	v_pk_fma_f32 v[206:207], v[172:173], v[220:221], v[206:207] op_sel_hi:[0,1,1]
	v_pk_fma_f32 v[208:209], v[172:173], v[222:223], v[208:209] op_sel_hi:[0,1,1]
	v_pk_fma_f32 v[210:211], v[172:173], v[224:225], v[210:211] op_sel_hi:[0,1,1]
	v_cvt_pk_f32_fp8_sdwa v[220:221], v110 src0_sel:WORD_1
	v_cvt_pk_f32_fp8_e32 v[222:223], v111
	v_cvt_pk_f32_fp8_sdwa v[224:225], v111 src0_sel:WORD_1
	v_pk_fma_f32 v[212:213], v[172:173], v[218:219], v[212:213] op_sel_hi:[0,1,1]
	v_cvt_pk_f32_fp8_e32 v[218:219], v104
	v_pk_fma_f32 v[214:215], v[172:173], v[220:221], v[214:215] op_sel_hi:[0,1,1]
	v_pk_fma_f32 v[216:217], v[172:173], v[222:223], v[216:217] op_sel_hi:[0,1,1]
	v_pk_fma_f32 v[140:141], v[172:173], v[224:225], v[140:141] op_sel_hi:[0,1,1]
	v_cvt_pk_f32_fp8_sdwa v[220:221], v104 src0_sel:WORD_1
	v_cvt_pk_f32_fp8_e32 v[222:223], v105
	v_cvt_pk_f32_fp8_sdwa v[224:225], v105 src0_sel:WORD_1
	v_and_b32_e32 v172, 0xffff0000, v200
	v_pk_fma_f32 v[174:175], v[172:173], v[218:219], v[174:175] op_sel_hi:[0,1,1]
	v_cvt_pk_f32_fp8_e32 v[218:219], v106
	v_pk_fma_f32 v[206:207], v[172:173], v[220:221], v[206:207] op_sel_hi:[0,1,1]
	v_pk_fma_f32 v[208:209], v[172:173], v[222:223], v[208:209] op_sel_hi:[0,1,1]
	v_pk_fma_f32 v[210:211], v[172:173], v[224:225], v[210:211] op_sel_hi:[0,1,1]
	v_cvt_pk_f32_fp8_sdwa v[220:221], v106 src0_sel:WORD_1
	v_cvt_pk_f32_fp8_e32 v[222:223], v107
	v_cvt_pk_f32_fp8_sdwa v[224:225], v107 src0_sel:WORD_1
	v_pk_fma_f32 v[212:213], v[172:173], v[218:219], v[212:213] op_sel_hi:[0,1,1]
	v_cvt_pk_f32_fp8_e32 v[218:219], v116
	v_pk_fma_f32 v[214:215], v[172:173], v[220:221], v[214:215] op_sel_hi:[0,1,1]
	v_pk_fma_f32 v[216:217], v[172:173], v[222:223], v[216:217] op_sel_hi:[0,1,1]
	v_pk_fma_f32 v[140:141], v[172:173], v[224:225], v[140:141] op_sel_hi:[0,1,1]
	v_cvt_pk_f32_fp8_sdwa v[220:221], v116 src0_sel:WORD_1
	v_cvt_pk_f32_fp8_e32 v[222:223], v117
	v_cvt_pk_f32_fp8_sdwa v[224:225], v117 src0_sel:WORD_1
	v_and_b32_e32 v172, 0xffff0000, v201
	v_pk_fma_f32 v[174:175], v[172:173], v[218:219], v[174:175] op_sel_hi:[0,1,1]
	v_cvt_pk_f32_fp8_e32 v[218:219], v118
	v_pk_fma_f32 v[206:207], v[172:173], v[220:221], v[206:207] op_sel_hi:[0,1,1]
	v_pk_fma_f32 v[208:209], v[172:173], v[222:223], v[208:209] op_sel_hi:[0,1,1]
	v_pk_fma_f32 v[210:211], v[172:173], v[224:225], v[210:211] op_sel_hi:[0,1,1]
	v_cvt_pk_f32_fp8_sdwa v[220:221], v118 src0_sel:WORD_1
	v_cvt_pk_f32_fp8_e32 v[222:223], v119
	v_cvt_pk_f32_fp8_sdwa v[224:225], v119 src0_sel:WORD_1
	v_pk_fma_f32 v[212:213], v[172:173], v[218:219], v[212:213] op_sel_hi:[0,1,1]
	v_cvt_pk_f32_fp8_e32 v[218:219], v112
	v_pk_fma_f32 v[214:215], v[172:173], v[220:221], v[214:215] op_sel_hi:[0,1,1]
	v_pk_fma_f32 v[216:217], v[172:173], v[222:223], v[216:217] op_sel_hi:[0,1,1]
	v_pk_fma_f32 v[140:141], v[172:173], v[224:225], v[140:141] op_sel_hi:[0,1,1]
	v_cvt_pk_f32_fp8_sdwa v[220:221], v112 src0_sel:WORD_1
	v_cvt_pk_f32_fp8_e32 v[222:223], v113
	v_cvt_pk_f32_fp8_sdwa v[224:225], v113 src0_sel:WORD_1
	v_and_b32_e32 v172, 0xffff0000, v202
	v_pk_fma_f32 v[174:175], v[172:173], v[218:219], v[174:175] op_sel_hi:[0,1,1]
	v_cvt_pk_f32_fp8_e32 v[218:219], v114
	v_pk_fma_f32 v[206:207], v[172:173], v[220:221], v[206:207] op_sel_hi:[0,1,1]
	v_pk_fma_f32 v[208:209], v[172:173], v[222:223], v[208:209] op_sel_hi:[0,1,1]
	v_pk_fma_f32 v[210:211], v[172:173], v[224:225], v[210:211] op_sel_hi:[0,1,1]
	v_cvt_pk_f32_fp8_sdwa v[220:221], v114 src0_sel:WORD_1
	v_cvt_pk_f32_fp8_e32 v[222:223], v115
	v_cvt_pk_f32_fp8_sdwa v[224:225], v115 src0_sel:WORD_1
	v_pk_fma_f32 v[212:213], v[172:173], v[218:219], v[212:213] op_sel_hi:[0,1,1]
	v_cvt_pk_f32_fp8_e32 v[218:219], v124
	v_pk_fma_f32 v[214:215], v[172:173], v[220:221], v[214:215] op_sel_hi:[0,1,1]
	v_pk_fma_f32 v[216:217], v[172:173], v[222:223], v[216:217] op_sel_hi:[0,1,1]
	v_pk_fma_f32 v[140:141], v[172:173], v[224:225], v[140:141] op_sel_hi:[0,1,1]
	v_cvt_pk_f32_fp8_sdwa v[220:221], v124 src0_sel:WORD_1
	v_cvt_pk_f32_fp8_e32 v[222:223], v125
	v_cvt_pk_f32_fp8_sdwa v[224:225], v125 src0_sel:WORD_1
	v_and_b32_e32 v172, 0xffff0000, v203
	v_pk_fma_f32 v[174:175], v[172:173], v[218:219], v[174:175] op_sel_hi:[0,1,1]
	v_cvt_pk_f32_fp8_e32 v[218:219], v126
	v_pk_fma_f32 v[206:207], v[172:173], v[220:221], v[206:207] op_sel_hi:[0,1,1]
	v_pk_fma_f32 v[208:209], v[172:173], v[222:223], v[208:209] op_sel_hi:[0,1,1]
	v_pk_fma_f32 v[210:211], v[172:173], v[224:225], v[210:211] op_sel_hi:[0,1,1]
	v_cvt_pk_f32_fp8_sdwa v[220:221], v126 src0_sel:WORD_1
	v_cvt_pk_f32_fp8_e32 v[222:223], v127
	v_cvt_pk_f32_fp8_sdwa v[224:225], v127 src0_sel:WORD_1
	v_pk_fma_f32 v[212:213], v[172:173], v[218:219], v[212:213] op_sel_hi:[0,1,1]
	v_cvt_pk_f32_fp8_e32 v[218:219], v120
	v_pk_fma_f32 v[214:215], v[172:173], v[220:221], v[214:215] op_sel_hi:[0,1,1]
	v_pk_fma_f32 v[216:217], v[172:173], v[222:223], v[216:217] op_sel_hi:[0,1,1]
	v_pk_fma_f32 v[140:141], v[172:173], v[224:225], v[140:141] op_sel_hi:[0,1,1]
	v_cvt_pk_f32_fp8_sdwa v[220:221], v120 src0_sel:WORD_1
	v_cvt_pk_f32_fp8_e32 v[222:223], v121
	v_cvt_pk_f32_fp8_sdwa v[224:225], v121 src0_sel:WORD_1
	v_and_b32_e32 v172, 0xffff0000, v204
	v_pk_fma_f32 v[174:175], v[172:173], v[218:219], v[174:175] op_sel_hi:[0,1,1]
	v_cvt_pk_f32_fp8_e32 v[218:219], v122
	v_pk_fma_f32 v[206:207], v[172:173], v[220:221], v[206:207] op_sel_hi:[0,1,1]
	v_pk_fma_f32 v[208:209], v[172:173], v[222:223], v[208:209] op_sel_hi:[0,1,1]
	v_pk_fma_f32 v[210:211], v[172:173], v[224:225], v[210:211] op_sel_hi:[0,1,1]
	v_cvt_pk_f32_fp8_sdwa v[220:221], v122 src0_sel:WORD_1
	v_cvt_pk_f32_fp8_e32 v[222:223], v123
	v_cvt_pk_f32_fp8_sdwa v[224:225], v123 src0_sel:WORD_1
	v_pk_fma_f32 v[212:213], v[172:173], v[218:219], v[212:213] op_sel_hi:[0,1,1]
	v_pk_fma_f32 v[214:215], v[172:173], v[220:221], v[214:215] op_sel_hi:[0,1,1]
	v_pk_fma_f32 v[216:217], v[172:173], v[222:223], v[216:217] op_sel_hi:[0,1,1]
	v_pk_fma_f32 v[140:141], v[172:173], v[224:225], v[140:141] op_sel_hi:[0,1,1]
	v_permlane32_swap_b32_e32 v174, v212
	v_permlane32_swap_b32_e32 v175, v213
	v_permlane32_swap_b32_e32 v208, v216
	v_permlane32_swap_b32_e32 v209, v217
	v_permlane32_swap_b32_e32 v206, v214
	v_permlane32_swap_b32_e32 v207, v215
	v_permlane32_swap_b32_e32 v210, v140
	v_permlane32_swap_b32_e32 v211, v141
	v_pk_add_f32 v[174:175], v[174:175], v[212:213]
	v_pk_add_f32 v[208:209], v[208:209], v[216:217]
	v_pk_add_f32 v[206:207], v[206:207], v[214:215]
	v_pk_add_f32 v[140:141], v[210:211], v[140:141]
	s_nop 1
	v_permlane16_swap_b32_e32 v174, v208
	v_permlane16_swap_b32_e32 v175, v209
	v_permlane16_swap_b32_e32 v206, v140
	v_permlane16_swap_b32_e32 v207, v141
	v_pk_add_f32 v[174:175], v[174:175], v[208:209]
	v_pk_add_f32 v[140:141], v[206:207], v[140:141]
	s_nop 1
	v_add_f32_dpp v140, v140, v140 row_ror:8 row_mask:0xf bank_mask:0xc
	v_add_f32_dpp v140, v174, v174 row_ror:8 row_mask:0xf bank_mask:0x3
	v_add_f32_dpp v141, v141, v141 row_ror:8 row_mask:0xf bank_mask:0xc
	v_add_f32_dpp v141, v175, v175 row_ror:8 row_mask:0xf bank_mask:0x3
	s_waitcnt lgkmcnt(0)
	v_ashrrev_i32_e32 v137, 31, v136
	v_lshlrev_b64 v[174:175], 12, v[136:137]
	v_lshl_add_u64 v[174:175], v[132:133], 0, v[174:175]
	v_pk_add_f32 v[134:135], v[140:141], v[134:135]
	global_store_dwordx2 v[174:175], v[134:135], off
	v_pk_mul_f32 v[134:135], v[134:135], v[134:135]
	s_nop 0
	v_add_f32_e32 v134, v134, v135
	v_mov_b32_e32 v135, 0
	s_nop 0
	v_add_f32_dpp v134, v134, v134 quad_perm:[1,0,3,2] row_mask:0xf bank_mask:0xf bound_ctrl:1
	s_nop 1
	v_add_f32_dpp v134, v134, v134 quad_perm:[2,3,0,1] row_mask:0xf bank_mask:0xf bound_ctrl:1
	s_nop 1
	v_add_f32_dpp v134, v134, v134 row_half_mirror row_mask:0xf bank_mask:0xf bound_ctrl:1
	s_nop 1
	v_add_f32_dpp v134, v134, v134 row_mirror row_mask:0xf bank_mask:0xf bound_ctrl:1
	s_nop 1
	v_mov_b32_dpp v135, v134 row_bcast:15 row_mask:0xa bank_mask:0xf
	v_add_f32_e32 v134, v134, v135
	v_mov_b32_e32 v135, 0
	s_nop 1
	v_mov_b32_dpp v135, v134 row_bcast:31 row_mask:0xc bank_mask:0xf
	v_add_f32_e32 v134, v134, v135
	s_nop 0
	v_readlane_b32 s12, v134, 63
	s_and_saveexec_b64 s[8:9], s[6:7]
	s_cbranch_execz .LBB0_1145
	v_lshl_add_u64 v[134:135], v[136:137], 2, s[30:31]
	v_mov_b32_e32 v137, s12
	global_store_dword v[134:135], v137, off
	s_branch .LBB0_1145
